# non-temporal f32 weight loads in the bf16 conversion items
# baseline (speedup 1.0000x reference)
.LBB0_22:
	s_cmpk_gt_i32 s57, 0x57f
	s_cselect_b64 s[2:3], -1, 0
	s_and_b64 vcc, exec, s[2:3]
	s_cbranch_vccnz .LBB0_21
	s_mul_hi_i32 s16, s57, 0xae4c415d
	s_add_i32 s16, s16, s57
	s_lshr_b32 s17, s16, 31
	s_ashr_i32 s58, s16, 12
	s_add_i32 s58, s58, s17
	s_mul_i32 s16, s58, 0x1780
	s_sub_i32 s18, s57, s16
	s_mul_i32 s17, s58, 0xb00000
	s_mul_hi_i32 s16, s58, 0xb00000
	s_add_u32 s19, s6, s17
	s_addc_u32 s59, s7, s16
	s_lshl_b32 s16, s58, 10
	s_ashr_i32 s17, s16, 31
	s_lshl_b64 s[16:17], s[16:17], 2
	s_add_u32 s20, s4, s16
	s_mul_i32 s16, s18, 0xba3
	s_addc_u32 s21, s5, s17
	s_lshr_b32 s17, s16, 31
	s_ashr_i32 s16, s16, 18
	s_add_i32 s16, s16, s17
	s_mul_i32 s17, s16, 0x58
	s_sub_i32 s17, s18, s17
	s_sext_i32_i16 s17, s17
	s_lshl_b32 s18, s16, 6
	s_lshl_b32 s16, s17, 5
	s_ashr_i32 s17, s16, 31
	s_lshl_b64 s[22:23], s[16:17], 2
	v_or_b32_e32 v10, s18, v4
	s_add_u32 s22, s19, s22
	s_addc_u32 s23, s59, s23
	v_mul_i32_i24_e32 v26, 0xb00, v10
	v_lshl_add_u64 v[22:23], s[22:23], 0, v[6:7]
	v_mul_hi_i32_i24_e32 v25, 0x2c00, v10
	v_mul_i32_i24_e32 v24, 0x2c00, v10
	v_ashrrev_i32_e32 v27, 31, v26
	v_lshl_add_u64 v[24:25], v[22:23], 0, v[24:25]
	v_lshl_add_u64 v[22:23], v[26:27], 2, v[22:23]
	v_add_co_u32_e32 v26, vcc, s26, v22
	s_nop 1
	v_addc_co_u32_e32 v27, vcc, 0, v23, vcc
	v_add_co_u32_e32 v28, vcc, s27, v22
	s_nop 1
	v_addc_co_u32_e32 v29, vcc, 0, v23, vcc
	v_add_co_u32_e32 v30, vcc, s28, v22
	s_nop 1
	v_addc_co_u32_e32 v31, vcc, 0, v23, vcc
	v_add_co_u32_e32 v32, vcc, s29, v22
	s_nop 1
	v_addc_co_u32_e32 v33, vcc, 0, v23, vcc
	v_add_co_u32_e32 v34, vcc, s30, v22
	s_nop 1
	v_addc_co_u32_e32 v35, vcc, 0, v23, vcc
	v_add_co_u32_e32 v38, vcc, s31, v22
	s_nop 1
	v_addc_co_u32_e32 v39, vcc, 0, v23, vcc
	v_add_co_u32_e32 v40, vcc, s34, v22
	s_nop 1
	v_addc_co_u32_e32 v41, vcc, 0, v23, vcc
	global_load_dword v52, v[24:25], off nt
	global_load_dword v53, v[26:27], off offset:2048 nt
	global_load_dword v51, v[28:29], off nt
	global_load_dword v50, v[30:31], off offset:2048 nt
	global_load_dword v47, v[32:33], off nt
	global_load_dword v49, v[34:35], off offset:2048 nt
	global_load_dword v48, v[38:39], off nt
	global_load_dword v46, v[40:41], off offset:2048 nt
	v_add_co_u32_e32 v24, vcc, s35, v22
	s_nop 1
	v_addc_co_u32_e32 v25, vcc, 0, v23, vcc
	v_add_co_u32_e32 v26, vcc, s36, v22
	s_nop 1
	v_addc_co_u32_e32 v27, vcc, 0, v23, vcc
	v_add_co_u32_e32 v28, vcc, s37, v22
	s_nop 1
	v_addc_co_u32_e32 v29, vcc, 0, v23, vcc
	v_add_co_u32_e32 v30, vcc, s38, v22
	s_nop 1
	v_addc_co_u32_e32 v31, vcc, 0, v23, vcc
	v_add_co_u32_e32 v32, vcc, s39, v22
	s_nop 1
	v_addc_co_u32_e32 v33, vcc, 0, v23, vcc
	v_add_co_u32_e32 v34, vcc, s40, v22
	s_nop 1
	v_addc_co_u32_e32 v35, vcc, 0, v23, vcc
	v_add_co_u32_e32 v54, vcc, s41, v22
	s_nop 1
	v_addc_co_u32_e32 v55, vcc, 0, v23, vcc
	v_add_co_u32_e32 v56, vcc, s42, v22
	s_nop 1
	v_addc_co_u32_e32 v57, vcc, 0, v23, vcc
	global_load_dword v43, v[24:25], off nt
	global_load_dword v45, v[26:27], off offset:2048 nt
	global_load_dword v44, v[28:29], off nt
	global_load_dword v42, v[30:31], off offset:2048 nt
	global_load_dword v39, v[32:33], off nt
	global_load_dword v41, v[34:35], off offset:2048 nt
	global_load_dword v40, v[54:55], off nt
	global_load_dword v38, v[56:57], off offset:2048 nt
	v_add_co_u32_e32 v24, vcc, s43, v22
	s_nop 1
	v_addc_co_u32_e32 v25, vcc, 0, v23, vcc
	v_add_co_u32_e32 v26, vcc, s44, v22
	s_nop 1
	v_addc_co_u32_e32 v27, vcc, 0, v23, vcc
	v_add_co_u32_e32 v28, vcc, s45, v22
	s_nop 1
	v_addc_co_u32_e32 v29, vcc, 0, v23, vcc
	v_add_co_u32_e32 v30, vcc, s46, v22
	s_nop 1
	v_addc_co_u32_e32 v31, vcc, 0, v23, vcc
	v_add_co_u32_e32 v54, vcc, s47, v22
	s_nop 1
	v_addc_co_u32_e32 v55, vcc, 0, v23, vcc
	v_add_co_u32_e32 v56, vcc, s49, v22
	s_nop 1
	v_addc_co_u32_e32 v57, vcc, 0, v23, vcc
	v_add_co_u32_e32 v58, vcc, s50, v22
	s_nop 1
	v_addc_co_u32_e32 v59, vcc, 0, v23, vcc
	v_add_co_u32_e32 v60, vcc, s51, v22
	s_nop 1
	v_addc_co_u32_e32 v61, vcc, 0, v23, vcc
	global_load_dword v34, v[24:25], off nt
	global_load_dword v37, v[26:27], off offset:2048 nt
	global_load_dword v35, v[28:29], off nt
	global_load_dword v33, v[30:31], off offset:2048 nt
	s_nop 0
	global_load_dword v30, v[54:55], off nt
	global_load_dword v32, v[56:57], off offset:2048 nt
	global_load_dword v31, v[58:59], off nt
	global_load_dword v28, v[60:61], off offset:2048 nt
	v_add_co_u32_e32 v24, vcc, s52, v22
	s_nop 1
	v_addc_co_u32_e32 v25, vcc, 0, v23, vcc
	v_add_co_u32_e32 v54, vcc, s53, v22
	s_nop 1
	v_addc_co_u32_e32 v55, vcc, 0, v23, vcc
	v_add_co_u32_e32 v56, vcc, s54, v22
	s_nop 1
	v_addc_co_u32_e32 v57, vcc, 0, v23, vcc
	v_add_co_u32_e32 v58, vcc, s55, v22
	s_nop 1
	v_addc_co_u32_e32 v59, vcc, 0, v23, vcc
	v_add_co_u32_e32 v60, vcc, s56, v22
	s_nop 1
	v_addc_co_u32_e32 v61, vcc, 0, v23, vcc
	v_add_co_u32_e32 v62, vcc, 0x9f000, v22
	s_nop 1
	v_addc_co_u32_e32 v63, vcc, 0, v23, vcc
	v_add_co_u32_e32 v64, vcc, 0xa5000, v22
	s_nop 1
	v_addc_co_u32_e32 v65, vcc, 0, v23, vcc
	v_add_co_u32_e32 v66, vcc, 0xaa000, v22
	s_nop 1
	v_addc_co_u32_e32 v67, vcc, 0, v23, vcc
	global_load_dword v26, v[24:25], off nt
	global_load_dword v29, v[54:55], off offset:2048 nt
	global_load_dword v27, v[56:57], off nt
	s_nop 0
	global_load_dword v25, v[58:59], off offset:2048 nt
	global_load_dword v23, v[60:61], off nt
	global_load_dword v24, v[62:63], off offset:2048 nt
	global_load_dword v22, v[64:65], off nt
	global_load_dword v9, v[66:67], off offset:2048 nt
	s_and_b64 vcc, exec, s[0:1]
	s_cbranch_vccnz .LBB0_46
	v_ashrrev_i32_e32 v11, 31, v10
	v_lshl_add_u64 v[10:11], v[10:11], 2, s[20:21]
	s_ashr_i32 s19, s18, 31
	global_load_dword v54, v[10:11], off nt
	v_lshl_add_u64 v[10:11], s[18:19], 0, v[4:5]
	v_lshl_add_u64 v[10:11], v[10:11], 2, s[20:21]
	global_load_dword v55, v[10:11], off offset:8 nt
	global_load_dword v56, v[10:11], off offset:16 nt
	s_nop 0
	global_load_dword v10, v[10:11], off offset:24 nt
	s_waitcnt vmcnt(3)
	v_mul_f32_e32 v11, v52, v54
	ds_write_b32 v18, v11
	s_waitcnt vmcnt(2)
	v_mul_f32_e32 v54, v53, v55
	s_waitcnt vmcnt(1)
	v_mul_f32_e32 v11, v51, v56
	ds_write_b32 v19, v54
	s_cbranch_execnz .LBB0_26

.LBB0_26:
	s_waitcnt vmcnt(0)
	v_mul_f32_e32 v10, v50, v10
	s_and_b64 vcc, exec, s[0:1]
	ds_write2_b32 v16, v11, v10 offset1:66
	s_cbranch_vccnz .LBB0_47
	s_ashr_i32 s19, s18, 31
	v_lshl_add_u64 v[10:11], s[18:19], 0, v[4:5]
	v_lshl_add_u64 v[10:11], v[10:11], 2, s[20:21]
	global_load_dword v50, v[10:11], off offset:32 nt
	global_load_dword v51, v[10:11], off offset:40 nt
	global_load_dword v52, v[10:11], off offset:48 nt
	s_nop 0
	global_load_dword v10, v[10:11], off offset:56 nt
	s_waitcnt vmcnt(3)
	v_mul_f32_e32 v50, v47, v50
	s_waitcnt vmcnt(2)
	v_mul_f32_e32 v51, v49, v51
	s_waitcnt vmcnt(1)
	v_mul_f32_e32 v11, v48, v52
	ds_write2_b32 v20, v50, v51 offset1:66
	s_cbranch_execnz .LBB0_29

.LBB0_29:
	s_waitcnt vmcnt(0)
	v_mul_f32_e32 v10, v46, v10
	s_and_b64 vcc, exec, s[0:1]
	ds_write2_b32 v17, v11, v10 offset1:66
	s_cbranch_vccnz .LBB0_48
	s_ashr_i32 s19, s18, 31
	v_lshl_add_u64 v[10:11], s[18:19], 0, v[4:5]
	v_lshl_add_u64 v[10:11], v[10:11], 2, s[20:21]
	global_load_dword v46, v[10:11], off offset:64 nt
	global_load_dword v47, v[10:11], off offset:72 nt
	global_load_dword v48, v[10:11], off offset:80 nt
	s_nop 0
	global_load_dword v10, v[10:11], off offset:88 nt
	s_waitcnt vmcnt(3)
	v_mul_f32_e32 v46, v43, v46
	s_waitcnt vmcnt(2)
	v_mul_f32_e32 v47, v45, v47
	s_waitcnt vmcnt(1)
	v_mul_f32_e32 v11, v44, v48
	ds_write2_b32 v21, v46, v47 offset1:66
	s_cbranch_execnz .LBB0_32

.LBB0_32:
	s_waitcnt vmcnt(0)
	v_mul_f32_e32 v10, v42, v10
	ds_write2_b32 v21, v11, v10 offset0:132 offset1:198
	s_and_b64 vcc, exec, s[0:1]
	v_add_u32_e32 v10, 0x400, v21
	s_cbranch_vccnz .LBB0_49
	s_ashr_i32 s19, s18, 31
	v_lshl_add_u64 v[42:43], s[18:19], 0, v[4:5]
	v_lshl_add_u64 v[42:43], v[42:43], 2, s[20:21]
	global_load_dword v44, v[42:43], off offset:96 nt
	global_load_dword v45, v[42:43], off offset:104 nt
	global_load_dword v46, v[42:43], off offset:112 nt
	global_load_dword v11, v[42:43], off offset:120 nt
	s_waitcnt vmcnt(3)
	v_mul_f32_e32 v43, v39, v44
	s_waitcnt vmcnt(2)
	v_mul_f32_e32 v44, v41, v45
	s_waitcnt vmcnt(1)
	v_mul_f32_e32 v42, v40, v46
	ds_write2_b32 v10, v43, v44 offset0:8 offset1:74
	s_cbranch_execnz .LBB0_35

.LBB0_35:
	s_waitcnt vmcnt(0)
	v_mul_f32_e32 v11, v38, v11
	ds_write2_b32 v10, v42, v11 offset0:140 offset1:206
	s_and_b64 vcc, exec, s[0:1]
	v_add_u32_e32 v10, 0x800, v21
	s_cbranch_vccnz .LBB0_50
	s_ashr_i32 s19, s18, 31
	v_lshl_add_u64 v[38:39], s[18:19], 0, v[4:5]
	v_lshl_add_u64 v[38:39], v[38:39], 2, s[20:21]
	global_load_dword v40, v[38:39], off offset:128 nt
	global_load_dword v41, v[38:39], off offset:136 nt
	global_load_dword v42, v[38:39], off offset:144 nt
	global_load_dword v11, v[38:39], off offset:152 nt
	s_waitcnt vmcnt(3)
	v_mul_f32_e32 v39, v34, v40
	s_waitcnt vmcnt(2)
	v_mul_f32_e32 v40, v37, v41
	s_waitcnt vmcnt(1)
	v_mul_f32_e32 v38, v35, v42
	ds_write2_b32 v10, v39, v40 offset0:16 offset1:82
	s_cbranch_execnz .LBB0_38

.LBB0_38:
	s_waitcnt vmcnt(0)
	v_mul_f32_e32 v11, v33, v11
	ds_write2_b32 v10, v38, v11 offset0:148 offset1:214
	s_and_b64 vcc, exec, s[0:1]
	v_add_u32_e32 v10, 0xc00, v21
	s_cbranch_vccnz .LBB0_51
	s_ashr_i32 s19, s18, 31
	v_lshl_add_u64 v[34:35], s[18:19], 0, v[4:5]
	v_lshl_add_u64 v[34:35], v[34:35], 2, s[20:21]
	global_load_dword v33, v[34:35], off offset:160 nt
	global_load_dword v37, v[34:35], off offset:168 nt
	global_load_dword v38, v[34:35], off offset:176 nt
	global_load_dword v11, v[34:35], off offset:184 nt
	s_waitcnt vmcnt(3)
	v_mul_f32_e32 v34, v30, v33
	s_waitcnt vmcnt(2)
	v_mul_f32_e32 v35, v32, v37
	s_waitcnt vmcnt(1)
	v_mul_f32_e32 v33, v31, v38
	ds_write2_b32 v10, v34, v35 offset0:24 offset1:90
	s_cbranch_execnz .LBB0_41

.LBB0_41:
	s_waitcnt vmcnt(0)
	v_mul_f32_e32 v11, v28, v11
	ds_write2_b32 v10, v33, v11 offset0:156 offset1:222
	s_and_b64 vcc, exec, s[0:1]
	v_add_u32_e32 v10, 0x1000, v21
	s_cbranch_vccnz .LBB0_52
	s_ashr_i32 s19, s18, 31
	v_lshl_add_u64 v[30:31], s[18:19], 0, v[4:5]
	v_lshl_add_u64 v[30:31], v[30:31], 2, s[20:21]
	global_load_dword v28, v[30:31], off offset:192 nt
	global_load_dword v32, v[30:31], off offset:200 nt
	global_load_dword v33, v[30:31], off offset:208 nt
	global_load_dword v11, v[30:31], off offset:216 nt
	s_waitcnt vmcnt(3)
	v_mul_f32_e32 v30, v26, v28
	s_waitcnt vmcnt(2)
	v_mul_f32_e32 v31, v29, v32
	s_waitcnt vmcnt(1)
	v_mul_f32_e32 v28, v27, v33
	ds_write2_b32 v10, v30, v31 offset0:32 offset1:98
	s_cbranch_execnz .LBB0_44

.LBB0_44:
	s_waitcnt vmcnt(0)
	v_mul_f32_e32 v11, v25, v11
	ds_write2_b32 v10, v28, v11 offset0:164 offset1:230
	s_and_b64 vcc, exec, s[0:1]
	v_add_u32_e32 v10, 0x1400, v21
	s_cbranch_vccnz .LBB0_53
	s_ashr_i32 s19, s18, 31
	v_lshl_add_u64 v[26:27], s[18:19], 0, v[4:5]
	v_lshl_add_u64 v[26:27], v[26:27], 2, s[20:21]
	global_load_dword v25, v[26:27], off offset:224 nt
	global_load_dword v28, v[26:27], off offset:232 nt
	global_load_dword v29, v[26:27], off offset:240 nt
	global_load_dword v11, v[26:27], off offset:248 nt
	s_waitcnt vmcnt(3)
	v_mul_f32_e32 v26, v23, v25
	s_waitcnt vmcnt(2)
	v_mul_f32_e32 v27, v24, v28
	s_waitcnt vmcnt(1)
	v_mul_f32_e32 v25, v22, v29
	ds_write2_b32 v10, v26, v27 offset0:40 offset1:106
	s_cbranch_execnz .LBB0_20
	s_branch .LBB0_19

.LBB0_124:
	v_readlane_b32 s0, v253, 26
	s_cmp_ge_i32 s7, s0
	v_readlane_b32 s0, v253, 36
	s_cselect_b32 s0, s0, 0
	s_add_i32 s0, s0, s7
	v_readlane_b32 s1, v253, 24
	s_cmp_ge_i32 s0, s1
	s_mov_b32 s17, 2
	s_cbranch_scc1 .LBB0_185
	s_mul_hi_i32 s1, s0, 0xae4c415d
	s_add_i32 s1, s1, s0
	s_lshr_b32 s2, s1, 31
	s_ashr_i32 s1, s1, 12
	s_add_i32 s2, s1, s2
	s_mul_i32 s1, s2, 0x1780
	s_sub_i32 s15, s0, s1
	s_ashr_i32 s3, s2, 31
	s_cmpk_gt_i32 s15, 0x57f
	s_mov_b64 s[0:1], -1
	s_cbranch_scc0 .LBB0_159
	s_cmpk_gt_u32 s15, 0x77f
	s_cbranch_scc0 .LBB0_156
	s_lshl_b64 s[0:1], s[2:3], 24
	s_lshl_b64 s[4:5], s[2:3], 23
	s_cmpk_gt_u32 s15, 0xf7f
	s_mov_b64 s[18:19], -1
	s_cbranch_scc0 .LBB0_129
	v_readlane_b32 s68, v252, 1
	v_readlane_b32 s76, v252, 9
	v_readlane_b32 s77, v252, 10
	s_add_u32 s21, s76, s0
	s_addc_u32 s23, s77, s1
	v_readlane_b32 s8, v248, 38
	s_add_u32 s18, s8, s4
	v_readlane_b32 s8, v248, 39
	s_addc_u32 s19, s8, s5
	s_lshl_b32 s17, s15, 1
	s_add_i32 s17, s17, 0x1e100
	s_and_b32 s20, s17, 0x1ffc0
	s_lshl_b32 s17, s15, 5
	s_and_b32 s17, s17, 0x3e0
	s_lshl_b32 s22, s17, 2
	s_add_u32 s22, s21, s22
	v_or_b32_e32 v5, s20, v0
	s_addc_u32 s23, s23, 0
	v_mov_b32_e32 v3, v16
	v_lshl_add_u64 v[6:7], s[22:23], 0, v[2:3]
	v_lshlrev_b32_e32 v8, 12, v5
	v_mov_b32_e32 v9, v16
	v_lshl_add_u64 v[6:7], v[6:7], 0, v[8:9]
	s_movk_i32 s8, 0x2000
	v_add_co_u32_e32 v8, vcc, s8, v6
	s_movk_i32 s8, 0x4000
	s_nop 0
	v_addc_co_u32_e32 v9, vcc, 0, v7, vcc
	global_load_dword v3, v[6:7], off nt
	global_load_dword v5, v[8:9], off nt
	v_add_co_u32_e32 v8, vcc, s8, v6
	s_movk_i32 s8, 0x6000
	s_nop 0
	v_addc_co_u32_e32 v9, vcc, 0, v7, vcc
	global_load_dword v37, v[8:9], off nt
	v_add_co_u32_e32 v8, vcc, s8, v6
	s_mov_b32 s8, 0xa000
	s_nop 0
	v_addc_co_u32_e32 v9, vcc, 0, v7, vcc
	global_load_dword v38, v[8:9], off nt
	v_add_co_u32_e32 v8, vcc, s10, v6
	s_lshl_b32 s20, s20, 1
	s_nop 0
	v_addc_co_u32_e32 v9, vcc, 0, v7, vcc
	global_load_dword v39, v[8:9], off nt
	v_add_co_u32_e32 v8, vcc, s8, v6
	s_mov_b32 s8, 0xc000
	s_nop 0
	v_addc_co_u32_e32 v9, vcc, 0, v7, vcc
	global_load_dword v40, v[8:9], off nt
	v_add_co_u32_e32 v8, vcc, s8, v6
	s_mov_b32 s8, 0xe000
	s_nop 0
	v_addc_co_u32_e32 v9, vcc, 0, v7, vcc
	global_load_dword v41, v[8:9], off nt
	v_add_co_u32_e32 v8, vcc, s8, v6
	s_mov_b32 s8, 0x12000
	s_nop 0
	v_addc_co_u32_e32 v9, vcc, 0, v7, vcc
	global_load_dword v42, v[8:9], off nt
	v_add_co_u32_e32 v8, vcc, s11, v6
	s_add_u32 s18, s18, s20
	s_nop 0
	v_addc_co_u32_e32 v9, vcc, 0, v7, vcc
	global_load_dword v43, v[8:9], off nt
	v_add_co_u32_e32 v8, vcc, s8, v6
	s_mov_b32 s8, 0x14000
	s_nop 0
	v_addc_co_u32_e32 v9, vcc, 0, v7, vcc
	global_load_dword v44, v[8:9], off nt
	v_add_co_u32_e32 v8, vcc, s8, v6
	s_mov_b32 s8, 0x16000
	s_nop 0
	v_addc_co_u32_e32 v9, vcc, 0, v7, vcc
	global_load_dword v45, v[8:9], off nt
	v_add_co_u32_e32 v8, vcc, s8, v6
	s_mov_b32 s8, 0x1a000
	s_nop 0
	v_addc_co_u32_e32 v9, vcc, 0, v7, vcc
	global_load_dword v46, v[8:9], off nt
	v_add_co_u32_e32 v8, vcc, s28, v6
	s_addc_u32 s19, s19, 0
	s_nop 0
	v_addc_co_u32_e32 v9, vcc, 0, v7, vcc
	global_load_dword v47, v[8:9], off nt
	v_add_co_u32_e32 v8, vcc, s8, v6
	s_mov_b32 s8, 0x1c000
	s_nop 0
	v_addc_co_u32_e32 v9, vcc, 0, v7, vcc
	global_load_dword v48, v[8:9], off nt
	v_add_co_u32_e32 v8, vcc, s8, v6
	s_mov_b32 s8, 0x1e000
	s_nop 0
	v_addc_co_u32_e32 v9, vcc, 0, v7, vcc
	global_load_dword v49, v[8:9], off nt
	v_add_co_u32_e32 v8, vcc, s8, v6
	s_mov_b32 s8, 0x22000
	s_nop 0
	v_addc_co_u32_e32 v9, vcc, 0, v7, vcc
	global_load_dword v50, v[8:9], off nt
	v_add_co_u32_e32 v8, vcc, s29, v6
	v_readlane_b32 s69, v252, 2
	s_nop 0
	v_addc_co_u32_e32 v9, vcc, 0, v7, vcc
	global_load_dword v51, v[8:9], off nt
	v_add_co_u32_e32 v8, vcc, s8, v6
	s_mov_b32 s8, 0x24000
	s_nop 0
	v_addc_co_u32_e32 v9, vcc, 0, v7, vcc
	global_load_dword v52, v[8:9], off nt
	v_add_co_u32_e32 v8, vcc, s8, v6
	s_mov_b32 s8, 0x26000
	s_nop 0
	v_addc_co_u32_e32 v9, vcc, 0, v7, vcc
	global_load_dword v53, v[8:9], off nt
	v_add_co_u32_e32 v8, vcc, s8, v6
	s_mov_b32 s8, 0x2a000
	s_nop 0
	v_addc_co_u32_e32 v9, vcc, 0, v7, vcc
	global_load_dword v54, v[8:9], off nt
	v_add_co_u32_e32 v8, vcc, s30, v6
	v_readlane_b32 s70, v252, 3
	s_nop 0
	v_addc_co_u32_e32 v9, vcc, 0, v7, vcc
	global_load_dword v55, v[8:9], off nt
	v_add_co_u32_e32 v8, vcc, s8, v6
	s_mov_b32 s8, 0x2e000
	s_nop 0
	v_addc_co_u32_e32 v9, vcc, 0, v7, vcc
	global_load_dword v56, v[8:9], off nt
	v_add_co_u32_e32 v8, vcc, s12, v6
	v_readlane_b32 s71, v252, 4
	s_nop 0
	v_addc_co_u32_e32 v9, vcc, 0, v7, vcc
	global_load_dword v57, v[8:9], off nt
	v_add_co_u32_e32 v8, vcc, s8, v6
	s_mov_b32 s8, 0x32000
	s_nop 0
	v_addc_co_u32_e32 v9, vcc, 0, v7, vcc
	global_load_dword v58, v[8:9], off nt
	v_add_co_u32_e32 v8, vcc, s33, v6
	v_readlane_b32 s72, v252, 5
	s_nop 0
	v_addc_co_u32_e32 v9, vcc, 0, v7, vcc
	global_load_dword v59, v[8:9], off nt
	v_add_co_u32_e32 v8, vcc, s8, v6
	s_mov_b32 s8, 0x34000
	s_nop 0
	v_addc_co_u32_e32 v9, vcc, 0, v7, vcc
	global_load_dword v60, v[8:9], off nt
	v_add_co_u32_e32 v8, vcc, s8, v6
	s_mov_b32 s8, 0x36000
	s_nop 0
	v_addc_co_u32_e32 v9, vcc, 0, v7, vcc
	global_load_dword v61, v[8:9], off nt
	v_add_co_u32_e32 v8, vcc, s8, v6
	s_mov_b32 s8, 0x3a000
	s_nop 0
	v_addc_co_u32_e32 v9, vcc, 0, v7, vcc
	global_load_dword v62, v[8:9], off nt
	v_add_co_u32_e32 v8, vcc, s34, v6
	v_readlane_b32 s73, v252, 6
	s_nop 0
	v_addc_co_u32_e32 v9, vcc, 0, v7, vcc
	global_load_dword v63, v[8:9], off nt
	v_add_co_u32_e32 v8, vcc, s8, v6
	s_mov_b32 s8, 0x3c000
	s_nop 0
	v_addc_co_u32_e32 v9, vcc, 0, v7, vcc
	global_load_dword v64, v[8:9], off nt
	v_add_co_u32_e32 v8, vcc, s8, v6
	s_mov_b32 s8, 0x3e000
	s_nop 0
	v_addc_co_u32_e32 v9, vcc, 0, v7, vcc
	v_add_co_u32_e32 v6, vcc, s8, v6
	global_load_dword v8, v[8:9], off nt
	s_nop 0
	v_addc_co_u32_e32 v7, vcc, 0, v7, vcc
	global_load_dword v6, v[6:7], off nt
	s_waitcnt vmcnt(30)
	ds_write2_b32 v29, v3, v5 offset1:66
	s_waitcnt vmcnt(28)
	ds_write2_b32 v29, v37, v38 offset0:132 offset1:198
	s_waitcnt vmcnt(26)
	ds_write2_b32 v30, v39, v40 offset0:8 offset1:74
	s_waitcnt vmcnt(24)
	ds_write2_b32 v30, v41, v42 offset0:140 offset1:206
	s_waitcnt vmcnt(22)
	ds_write2_b32 v31, v43, v44 offset0:16 offset1:82
	s_waitcnt vmcnt(20)
	ds_write2_b32 v31, v45, v46 offset0:148 offset1:214
	s_waitcnt vmcnt(18)
	ds_write2_b32 v32, v47, v48 offset0:24 offset1:90
	s_waitcnt vmcnt(16)
	ds_write2_b32 v32, v49, v50 offset0:156 offset1:222
	s_waitcnt vmcnt(14)
	ds_write2_b32 v33, v51, v52 offset0:32 offset1:98
	s_waitcnt vmcnt(12)
	ds_write2_b32 v33, v53, v54 offset0:164 offset1:230
	s_waitcnt vmcnt(10)
	ds_write2_b32 v34, v55, v56 offset0:40 offset1:106
	s_waitcnt vmcnt(8)
	ds_write2_b32 v34, v57, v58 offset0:172 offset1:238
	s_waitcnt vmcnt(6)
	ds_write2_b32 v35, v59, v60 offset0:48 offset1:114
	s_waitcnt vmcnt(4)
	ds_write2_b32 v35, v61, v62 offset0:180 offset1:246
	s_waitcnt vmcnt(2)
	ds_write2_b32 v36, v63, v64 offset0:56 offset1:122
	s_waitcnt vmcnt(0)
	ds_write2_b32 v36, v8, v6 offset0:188 offset1:254
	s_waitcnt lgkmcnt(0)
	ds_read2_b32 v[6:7], v12 offset1:33
	s_waitcnt lgkmcnt(0)
	v_cvt_pk_bf16_f32 v6, v6, v7
	ds_read2_b32 v[8:9], v12 offset0:66 offset1:99
	s_waitcnt lgkmcnt(0)
	v_cvt_pk_bf16_f32 v7, v8, v9
	ds_read2_b32 v[8:9], v12 offset0:132 offset1:165
	v_mov_b32_e32 v5, v16
	s_waitcnt lgkmcnt(0)
	v_cvt_pk_bf16_f32 v8, v8, v9
	ds_read2_b32 v[40:41], v12 offset0:198 offset1:231
	v_or_b32_e32 v3, s17, v11
	v_lshl_add_u64 v[38:39], s[18:19], 0, v[4:5]
	s_waitcnt lgkmcnt(0)
	v_cvt_pk_bf16_f32 v9, v40, v41
	v_lshlrev_b32_e32 v40, 13, v3
	v_mov_b32_e32 v41, v16
	v_lshl_add_u64 v[40:41], v[38:39], 0, v[40:41]
	global_store_dwordx4 v[40:41], v[6:9], off
	ds_read2_b32 v[6:7], v12 offset0:8 offset1:41
	v_or_b32_e32 v3, s17, v13
	s_waitcnt lgkmcnt(0)
	v_cvt_pk_bf16_f32 v6, v6, v7
	ds_read2_b32 v[8:9], v12 offset0:74 offset1:107
	s_waitcnt lgkmcnt(0)
	v_cvt_pk_bf16_f32 v7, v8, v9
	ds_read2_b32 v[8:9], v12 offset0:140 offset1:173
	s_waitcnt lgkmcnt(0)
	v_cvt_pk_bf16_f32 v8, v8, v9
	ds_read2_b32 v[40:41], v12 offset0:206 offset1:239
	s_waitcnt lgkmcnt(0)
	v_cvt_pk_bf16_f32 v9, v40, v41
	v_lshlrev_b32_e32 v40, 13, v3
	v_mov_b32_e32 v41, v16
	v_lshl_add_u64 v[40:41], v[38:39], 0, v[40:41]
	global_store_dwordx4 v[40:41], v[6:9], off
	ds_read2_b32 v[6:7], v12 offset0:16 offset1:49
	v_or_b32_e32 v3, s17, v14
	s_waitcnt lgkmcnt(0)
	v_cvt_pk_bf16_f32 v6, v6, v7
	ds_read2_b32 v[8:9], v12 offset0:82 offset1:115
	s_waitcnt lgkmcnt(0)
	v_cvt_pk_bf16_f32 v7, v8, v9
	ds_read2_b32 v[8:9], v12 offset0:148 offset1:181
	s_waitcnt lgkmcnt(0)
	v_cvt_pk_bf16_f32 v8, v8, v9
	ds_read2_b32 v[40:41], v12 offset0:214 offset1:247
	s_waitcnt lgkmcnt(0)
	v_cvt_pk_bf16_f32 v9, v40, v41
	v_lshlrev_b32_e32 v40, 13, v3
	v_mov_b32_e32 v41, v16
	v_lshl_add_u64 v[40:41], v[38:39], 0, v[40:41]
	global_store_dwordx4 v[40:41], v[6:9], off
	ds_read2_b32 v[6:7], v12 offset0:24 offset1:57
	v_or_b32_e32 v3, s17, v15
	s_waitcnt lgkmcnt(0)
	v_cvt_pk_bf16_f32 v6, v6, v7
	ds_read2_b32 v[8:9], v12 offset0:90 offset1:123
	s_waitcnt lgkmcnt(0)
	v_cvt_pk_bf16_f32 v7, v8, v9
	ds_read2_b32 v[8:9], v12 offset0:156 offset1:189
	s_waitcnt lgkmcnt(0)
	v_cvt_pk_bf16_f32 v8, v8, v9
	ds_read2_b32 v[40:41], v12 offset0:222 offset1:255
	s_waitcnt lgkmcnt(0)
	v_cvt_pk_bf16_f32 v9, v40, v41
	v_lshlrev_b32_e32 v40, 13, v3
	v_mov_b32_e32 v41, v16
	v_lshl_add_u64 v[38:39], v[38:39], 0, v[40:41]
	global_store_dwordx4 v[38:39], v[6:9], off
	s_waitcnt lgkmcnt(0)
	v_readlane_b32 s74, v252, 7
	v_readlane_b32 s75, v252, 8
	v_readlane_b32 s78, v252, 11
	v_readlane_b32 s79, v252, 12
	v_readlane_b32 s80, v252, 13
	v_readlane_b32 s81, v252, 14
	v_readlane_b32 s82, v252, 15
	v_readlane_b32 s83, v252, 16
	s_mov_b64 s[18:19], 0
.LBB0_129:
	s_andn2_b64 vcc, exec, s[18:19]
	s_mov_b32 s17, 0
	s_cbranch_vccnz .LBB0_155
	v_readlane_b32 s68, v252, 1
	v_readlane_b32 s74, v252, 7
	v_readlane_b32 s75, v252, 8
	s_add_u32 s20, s74, s0
	s_addc_u32 s21, s75, s1
	s_lshl_b32 s0, s2, 10
	s_ashr_i32 s1, s0, 31
	v_readlane_b32 s72, v252, 5
	s_lshl_b64 s[0:1], s[0:1], 2
	v_readlane_b32 s73, v252, 6
	s_add_u32 s18, s72, s0
	s_addc_u32 s19, s73, s1
	s_add_i32 s0, s15, 0xf880
	s_lshr_b32 s0, s0, 1
	s_and_b32 s22, s0, 0x7fc0
	s_lshl_b32 s0, s15, 5
	s_and_b32 s17, s0, 0xfe0
	s_lshl_b32 s0, s17, 2
	s_add_u32 s0, s20, s0
	v_or_b32_e32 v64, s22, v0
	s_addc_u32 s1, s21, 0
	v_mov_b32_e32 v3, v16
	v_lshl_add_u64 v[6:7], s[0:1], 0, v[2:3]
	v_lshlrev_b32_e32 v8, 14, v64
	v_mov_b32_e32 v9, v16
	v_lshl_add_u64 v[6:7], v[6:7], 0, v[8:9]
	v_add_co_u32_e32 v8, vcc, s10, v6
	global_load_dword v60, v[6:7], off nt
	s_nop 0
	v_addc_co_u32_e32 v9, vcc, 0, v7, vcc
	global_load_dword v61, v[8:9], off nt
	v_add_co_u32_e32 v8, vcc, s11, v6
	s_mov_b32 s0, 0x40000
	s_nop 0
	v_addc_co_u32_e32 v9, vcc, 0, v7, vcc
	global_load_dword v62, v[8:9], off nt
	v_add_co_u32_e32 v8, vcc, s28, v6
	v_readlane_b32 s8, v248, 44
	s_nop 0
	v_addc_co_u32_e32 v9, vcc, 0, v7, vcc
	global_load_dword v63, v[8:9], off nt
	v_add_co_u32_e32 v8, vcc, s29, v6
	v_readlane_b32 s9, v248, 45
	s_nop 0
	v_addc_co_u32_e32 v9, vcc, 0, v7, vcc
	global_load_dword v56, v[8:9], off nt
	v_add_co_u32_e32 v8, vcc, s30, v6
	v_readlane_b32 s69, v252, 2
	s_nop 0
	v_addc_co_u32_e32 v9, vcc, 0, v7, vcc
	global_load_dword v57, v[8:9], off nt
	v_add_co_u32_e32 v8, vcc, s33, v6
	v_readlane_b32 s70, v252, 3
	s_nop 0
	v_addc_co_u32_e32 v9, vcc, 0, v7, vcc
	global_load_dword v58, v[8:9], off nt
	v_add_co_u32_e32 v8, vcc, s34, v6
	v_readlane_b32 s71, v252, 4
	s_nop 0
	v_addc_co_u32_e32 v9, vcc, 0, v7, vcc
	global_load_dword v59, v[8:9], off nt
	v_add_co_u32_e32 v8, vcc, s0, v6
	s_mov_b32 s0, 0x48000
	s_nop 0
	v_addc_co_u32_e32 v9, vcc, 0, v7, vcc
	global_load_dword v52, v[8:9], off nt
	v_add_co_u32_e32 v8, vcc, s0, v6
	s_mov_b32 s0, 0x50000
	s_nop 0
	v_addc_co_u32_e32 v9, vcc, 0, v7, vcc
	global_load_dword v53, v[8:9], off nt
	v_add_co_u32_e32 v8, vcc, s0, v6
	s_mov_b32 s0, 0x58000
	s_nop 0
	v_addc_co_u32_e32 v9, vcc, 0, v7, vcc
	global_load_dword v54, v[8:9], off nt
	v_add_co_u32_e32 v8, vcc, s0, v6
	s_mov_b32 s0, 0x60000
	s_nop 0
	v_addc_co_u32_e32 v9, vcc, 0, v7, vcc
	global_load_dword v55, v[8:9], off nt
	v_add_co_u32_e32 v8, vcc, s0, v6
	s_mov_b32 s0, 0x68000
	s_nop 0
	v_addc_co_u32_e32 v9, vcc, 0, v7, vcc
	global_load_dword v48, v[8:9], off nt
	v_add_co_u32_e32 v8, vcc, s0, v6
	s_mov_b32 s0, 0x70000
	s_nop 0
	v_addc_co_u32_e32 v9, vcc, 0, v7, vcc
	global_load_dword v49, v[8:9], off nt
	v_add_co_u32_e32 v8, vcc, s0, v6
	s_mov_b32 s0, 0x78000
	s_nop 0
	v_addc_co_u32_e32 v9, vcc, 0, v7, vcc
	global_load_dword v50, v[8:9], off nt
	v_add_co_u32_e32 v8, vcc, s0, v6
	s_mov_b32 s0, 0x80000
	s_nop 0
	v_addc_co_u32_e32 v9, vcc, 0, v7, vcc
	global_load_dword v51, v[8:9], off nt
	v_add_co_u32_e32 v8, vcc, s0, v6
	s_mov_b32 s0, 0x88000
	s_nop 0
	v_addc_co_u32_e32 v9, vcc, 0, v7, vcc
	global_load_dword v44, v[8:9], off nt
	v_add_co_u32_e32 v8, vcc, s0, v6
	s_mov_b32 s0, 0x90000
	s_nop 0
	v_addc_co_u32_e32 v9, vcc, 0, v7, vcc
	global_load_dword v45, v[8:9], off nt
	v_add_co_u32_e32 v8, vcc, s0, v6
	s_mov_b32 s0, 0x98000
	s_nop 0
	v_addc_co_u32_e32 v9, vcc, 0, v7, vcc
	global_load_dword v46, v[8:9], off nt
	v_add_co_u32_e32 v8, vcc, s0, v6
	s_mov_b32 s0, 0xa0000
	s_nop 0
	v_addc_co_u32_e32 v9, vcc, 0, v7, vcc
	global_load_dword v47, v[8:9], off nt
	v_add_co_u32_e32 v8, vcc, s0, v6
	s_mov_b32 s0, 0xa8000
	s_nop 0
	v_addc_co_u32_e32 v9, vcc, 0, v7, vcc
	global_load_dword v39, v[8:9], off nt
	v_add_co_u32_e32 v8, vcc, s0, v6
	s_mov_b32 s0, 0xb0000
	s_nop 0
	v_addc_co_u32_e32 v9, vcc, 0, v7, vcc
	global_load_dword v41, v[8:9], off nt
	v_add_co_u32_e32 v8, vcc, s0, v6
	s_mov_b32 s0, 0xb8000
	s_nop 0
	v_addc_co_u32_e32 v9, vcc, 0, v7, vcc
	global_load_dword v42, v[8:9], off nt
	v_add_co_u32_e32 v8, vcc, s0, v6
	s_mov_b32 s0, 0xc0000
	s_nop 0
	v_addc_co_u32_e32 v9, vcc, 0, v7, vcc
	global_load_dword v43, v[8:9], off nt
	v_add_co_u32_e32 v8, vcc, s0, v6
	s_mov_b32 s0, 0xc8000
	s_nop 0
	v_addc_co_u32_e32 v9, vcc, 0, v7, vcc
	v_add_co_u32_e32 v66, vcc, s0, v6
	s_mov_b32 s0, 0xd0000
	s_nop 0
	v_addc_co_u32_e32 v67, vcc, 0, v7, vcc
	global_load_dword v9, v[8:9], off nt
	v_readlane_b32 s76, v252, 9
	global_load_dword v37, v[66:67], off nt
	v_add_co_u32_e32 v66, vcc, s0, v6
	s_mov_b32 s0, 0xd8000
	s_nop 0
	v_addc_co_u32_e32 v67, vcc, 0, v7, vcc
	global_load_dword v38, v[66:67], off nt
	v_add_co_u32_e32 v66, vcc, s0, v6
	s_mov_b32 s0, 0xe0000
	s_nop 0
	v_addc_co_u32_e32 v67, vcc, 0, v7, vcc
	global_load_dword v40, v[66:67], off nt
	v_add_co_u32_e32 v66, vcc, s0, v6
	v_readlane_b32 s77, v252, 10
	s_nop 0
	v_addc_co_u32_e32 v67, vcc, 0, v7, vcc
	global_load_dword v3, v[66:67], off nt
	v_add_co_u32_e32 v66, vcc, 0xe8000, v6
	v_readlane_b32 s78, v252, 11
	s_nop 0
	v_addc_co_u32_e32 v67, vcc, 0, v7, vcc
	global_load_dword v5, v[66:67], off nt
	v_add_co_u32_e32 v66, vcc, 0xf0000, v6
	v_readlane_b32 s79, v252, 12
	s_nop 0
	v_addc_co_u32_e32 v67, vcc, 0, v7, vcc
	v_add_co_u32_e32 v6, vcc, 0xf8000, v6
	v_readlane_b32 s80, v252, 13
	s_nop 0
	v_addc_co_u32_e32 v7, vcc, 0, v7, vcc
	global_load_dword v6, v[6:7], off nt
	v_cndmask_b32_e64 v7, 0, 1, s[8:9]
	global_load_dword v8, v[66:67], off nt
	v_cmp_ne_u32_e64 s[0:1], 1, v7
	s_andn2_b64 vcc, exec, s[8:9]
	v_add_lshl_u32 v7, s22, v0, 2
	v_readlane_b32 s81, v252, 14
	v_readlane_b32 s82, v252, 15
	v_readlane_b32 s83, v252, 16
	s_cbranch_vccnz .LBB0_197
	v_lshlrev_b32_e32 v64, 2, v64
	global_load_dword v64, v64, s[18:19]
	s_nop 0
	global_load_dword v65, v7, s[18:19] offset:8
	s_waitcnt vmcnt(1)
	v_mul_f32_e32 v64, v60, v64
	ds_write_b32 v29, v64
	s_waitcnt vmcnt(0)
	v_mul_f32_e32 v64, v61, v65
	v_add_u32_e32 v65, v10, v18
	ds_write_b32 v65, v64
	global_load_dword v64, v7, s[18:19] offset:16
	global_load_dword v65, v7, s[18:19] offset:24
	s_waitcnt vmcnt(1)
	v_mul_f32_e32 v64, v62, v64
	s_cbranch_execnz .LBB0_133

.LBB0_156:
	s_andn2_b64 vcc, exec, s[0:1]
	s_cbranch_vccnz .LBB0_158
	v_readlane_b32 s68, v252, 1
	s_lshl_b64 s[0:1], s[2:3], 22
	v_readlane_b32 s70, v252, 3
	v_readlane_b32 s71, v252, 4
	s_add_u32 s17, s70, s0
	s_addc_u32 s19, s71, s1
	s_lshl_b64 s[4:5], s[2:3], 21
	v_readlane_b32 s0, v248, 42
	s_add_u32 s1, s0, s4
	v_readlane_b32 s0, v248, 43
	s_addc_u32 s3, s0, s5
	s_lshl_b32 s0, s15, 1
	s_add_i32 s0, s0, 0x1f500
	s_and_b32 s4, s0, 0x1ffc0
	s_lshl_b32 s0, s15, 5
	s_and_b32 s0, s0, 0x3e0
	s_lshl_b32 s5, s0, 2
	s_add_u32 s18, s17, s5
	v_or_b32_e32 v5, s4, v0
	s_addc_u32 s19, s19, 0
	v_mov_b32_e32 v3, v16
	v_lshl_add_u64 v[6:7], s[18:19], 0, v[2:3]
	v_lshlrev_b32_e32 v8, 12, v5
	v_mov_b32_e32 v9, v16
	v_lshl_add_u64 v[6:7], v[6:7], 0, v[8:9]
	s_movk_i32 s5, 0x2000
	v_add_co_u32_e32 v8, vcc, s5, v6
	s_movk_i32 s5, 0x4000
	s_nop 0
	v_addc_co_u32_e32 v9, vcc, 0, v7, vcc
	global_load_dword v3, v[6:7], off nt
	global_load_dword v5, v[8:9], off nt
	v_add_co_u32_e32 v8, vcc, s5, v6
	s_movk_i32 s5, 0x6000
	s_nop 0
	v_addc_co_u32_e32 v9, vcc, 0, v7, vcc
	global_load_dword v37, v[8:9], off nt
	v_add_co_u32_e32 v8, vcc, s5, v6
	s_mov_b32 s5, 0xa000
	s_nop 0
	v_addc_co_u32_e32 v9, vcc, 0, v7, vcc
	global_load_dword v38, v[8:9], off nt
	v_add_co_u32_e32 v8, vcc, s10, v6
	s_lshl_b32 s4, s4, 1
	s_nop 0
	v_addc_co_u32_e32 v9, vcc, 0, v7, vcc
	global_load_dword v39, v[8:9], off nt
	v_add_co_u32_e32 v8, vcc, s5, v6
	s_mov_b32 s5, 0xc000
	s_nop 0
	v_addc_co_u32_e32 v9, vcc, 0, v7, vcc
	global_load_dword v40, v[8:9], off nt
	v_add_co_u32_e32 v8, vcc, s5, v6
	s_mov_b32 s5, 0xe000
	s_nop 0
	v_addc_co_u32_e32 v9, vcc, 0, v7, vcc
	global_load_dword v41, v[8:9], off nt
	v_add_co_u32_e32 v8, vcc, s5, v6
	s_mov_b32 s5, 0x12000
	s_nop 0
	v_addc_co_u32_e32 v9, vcc, 0, v7, vcc
	global_load_dword v42, v[8:9], off nt
	v_add_co_u32_e32 v8, vcc, s11, v6
	s_add_u32 s4, s1, s4
	s_nop 0
	v_addc_co_u32_e32 v9, vcc, 0, v7, vcc
	global_load_dword v43, v[8:9], off nt
	v_add_co_u32_e32 v8, vcc, s5, v6
	s_mov_b32 s5, 0x14000
	s_nop 0
	v_addc_co_u32_e32 v9, vcc, 0, v7, vcc
	global_load_dword v44, v[8:9], off nt
	v_add_co_u32_e32 v8, vcc, s5, v6
	s_mov_b32 s5, 0x16000
	s_nop 0
	v_addc_co_u32_e32 v9, vcc, 0, v7, vcc
	global_load_dword v45, v[8:9], off nt
	v_add_co_u32_e32 v8, vcc, s5, v6
	s_mov_b32 s5, 0x1a000
	s_nop 0
	v_addc_co_u32_e32 v9, vcc, 0, v7, vcc
	global_load_dword v46, v[8:9], off nt
	v_add_co_u32_e32 v8, vcc, s28, v6
	s_mov_b32 s17, 4
	s_nop 0
	v_addc_co_u32_e32 v9, vcc, 0, v7, vcc
	global_load_dword v47, v[8:9], off nt
	v_add_co_u32_e32 v8, vcc, s5, v6
	s_mov_b32 s5, 0x1c000
	s_nop 0
	v_addc_co_u32_e32 v9, vcc, 0, v7, vcc
	global_load_dword v48, v[8:9], off nt
	v_add_co_u32_e32 v8, vcc, s5, v6
	s_mov_b32 s5, 0x1e000
	s_nop 0
	v_addc_co_u32_e32 v9, vcc, 0, v7, vcc
	global_load_dword v49, v[8:9], off nt
	v_add_co_u32_e32 v8, vcc, s5, v6
	s_mov_b32 s5, 0x22000
	s_nop 0
	v_addc_co_u32_e32 v9, vcc, 0, v7, vcc
	global_load_dword v50, v[8:9], off nt
	v_add_co_u32_e32 v8, vcc, s29, v6
	v_readlane_b32 s69, v252, 2
	s_nop 0
	v_addc_co_u32_e32 v9, vcc, 0, v7, vcc
	global_load_dword v51, v[8:9], off nt
	v_add_co_u32_e32 v8, vcc, s5, v6
	s_mov_b32 s5, 0x24000
	s_nop 0
	v_addc_co_u32_e32 v9, vcc, 0, v7, vcc
	global_load_dword v52, v[8:9], off nt
	v_add_co_u32_e32 v8, vcc, s5, v6
	s_mov_b32 s5, 0x26000
	s_nop 0
	v_addc_co_u32_e32 v9, vcc, 0, v7, vcc
	global_load_dword v53, v[8:9], off nt
	v_add_co_u32_e32 v8, vcc, s5, v6
	s_mov_b32 s5, 0x2a000
	s_nop 0
	v_addc_co_u32_e32 v9, vcc, 0, v7, vcc
	global_load_dword v54, v[8:9], off nt
	v_add_co_u32_e32 v8, vcc, s30, v6
	v_readlane_b32 s72, v252, 5
	s_nop 0
	v_addc_co_u32_e32 v9, vcc, 0, v7, vcc
	global_load_dword v55, v[8:9], off nt
	v_add_co_u32_e32 v8, vcc, s5, v6
	s_mov_b32 s5, 0x2e000
	s_nop 0
	v_addc_co_u32_e32 v9, vcc, 0, v7, vcc
	global_load_dword v56, v[8:9], off nt
	v_add_co_u32_e32 v8, vcc, s12, v6
	v_readlane_b32 s73, v252, 6
	s_nop 0
	v_addc_co_u32_e32 v9, vcc, 0, v7, vcc
	global_load_dword v57, v[8:9], off nt
	v_add_co_u32_e32 v8, vcc, s5, v6
	s_mov_b32 s5, 0x32000
	s_nop 0
	v_addc_co_u32_e32 v9, vcc, 0, v7, vcc
	global_load_dword v58, v[8:9], off nt
	v_add_co_u32_e32 v8, vcc, s33, v6
	v_readlane_b32 s74, v252, 7
	s_nop 0
	v_addc_co_u32_e32 v9, vcc, 0, v7, vcc
	global_load_dword v59, v[8:9], off nt
	v_add_co_u32_e32 v8, vcc, s5, v6
	s_mov_b32 s5, 0x34000
	s_nop 0
	v_addc_co_u32_e32 v9, vcc, 0, v7, vcc
	global_load_dword v60, v[8:9], off nt
	v_add_co_u32_e32 v8, vcc, s5, v6
	s_mov_b32 s5, 0x36000
	s_nop 0
	v_addc_co_u32_e32 v9, vcc, 0, v7, vcc
	global_load_dword v61, v[8:9], off nt
	v_add_co_u32_e32 v8, vcc, s5, v6
	s_mov_b32 s5, 0x3a000
	s_nop 0
	v_addc_co_u32_e32 v9, vcc, 0, v7, vcc
	global_load_dword v62, v[8:9], off nt
	v_add_co_u32_e32 v8, vcc, s34, v6
	v_readlane_b32 s75, v252, 8
	s_nop 0
	v_addc_co_u32_e32 v9, vcc, 0, v7, vcc
	global_load_dword v63, v[8:9], off nt
	v_add_co_u32_e32 v8, vcc, s5, v6
	s_mov_b32 s5, 0x3c000
	s_nop 0
	v_addc_co_u32_e32 v9, vcc, 0, v7, vcc
	global_load_dword v64, v[8:9], off nt
	v_add_co_u32_e32 v8, vcc, s5, v6
	s_mov_b32 s5, 0x3e000
	s_nop 0
	v_addc_co_u32_e32 v9, vcc, 0, v7, vcc
	v_add_co_u32_e32 v6, vcc, s5, v6
	global_load_dword v8, v[8:9], off nt
	s_nop 0
	v_addc_co_u32_e32 v7, vcc, 0, v7, vcc
	global_load_dword v6, v[6:7], off nt
	s_waitcnt vmcnt(30)
	ds_write2_b32 v29, v3, v5 offset1:66
	s_waitcnt vmcnt(28)
	ds_write2_b32 v29, v37, v38 offset0:132 offset1:198
	s_waitcnt vmcnt(26)
	ds_write2_b32 v30, v39, v40 offset0:8 offset1:74
	s_waitcnt vmcnt(24)
	ds_write2_b32 v30, v41, v42 offset0:140 offset1:206
	s_waitcnt vmcnt(22)
	ds_write2_b32 v31, v43, v44 offset0:16 offset1:82
	s_waitcnt vmcnt(20)
	ds_write2_b32 v31, v45, v46 offset0:148 offset1:214
	s_waitcnt vmcnt(18)
	ds_write2_b32 v32, v47, v48 offset0:24 offset1:90
	s_waitcnt vmcnt(16)
	ds_write2_b32 v32, v49, v50 offset0:156 offset1:222
	s_waitcnt vmcnt(14)
	ds_write2_b32 v33, v51, v52 offset0:32 offset1:98
	s_waitcnt vmcnt(12)
	ds_write2_b32 v33, v53, v54 offset0:164 offset1:230
	s_waitcnt vmcnt(10)
	ds_write2_b32 v34, v55, v56 offset0:40 offset1:106
	s_waitcnt vmcnt(8)
	ds_write2_b32 v34, v57, v58 offset0:172 offset1:238
	s_waitcnt vmcnt(6)
	ds_write2_b32 v35, v59, v60 offset0:48 offset1:114
	s_waitcnt vmcnt(4)
	ds_write2_b32 v35, v61, v62 offset0:180 offset1:246
	s_waitcnt vmcnt(2)
	ds_write2_b32 v36, v63, v64 offset0:56 offset1:122
	s_waitcnt vmcnt(0)
	ds_write2_b32 v36, v8, v6 offset0:188 offset1:254
	s_waitcnt lgkmcnt(0)
	ds_read2_b32 v[6:7], v12 offset1:33
	s_waitcnt lgkmcnt(0)
	v_cvt_pk_bf16_f32 v6, v6, v7
	ds_read2_b32 v[8:9], v12 offset0:66 offset1:99
	s_waitcnt lgkmcnt(0)
	v_cvt_pk_bf16_f32 v7, v8, v9
	ds_read2_b32 v[8:9], v12 offset0:132 offset1:165
	s_addc_u32 s5, s3, 0
	v_mov_b32_e32 v5, v16
	s_waitcnt lgkmcnt(0)
	v_cvt_pk_bf16_f32 v8, v8, v9
	ds_read2_b32 v[40:41], v12 offset0:198 offset1:231
	v_or_b32_e32 v3, s0, v11
	v_lshl_add_u64 v[38:39], s[4:5], 0, v[4:5]
	s_waitcnt lgkmcnt(0)
	v_cvt_pk_bf16_f32 v9, v40, v41
	v_lshlrev_b32_e32 v40, 11, v3
	v_mov_b32_e32 v41, v16
	v_lshl_add_u64 v[40:41], v[38:39], 0, v[40:41]
	global_store_dwordx4 v[40:41], v[6:9], off
	ds_read2_b32 v[6:7], v12 offset0:8 offset1:41
	v_or_b32_e32 v3, s0, v13
	s_waitcnt lgkmcnt(0)
	v_cvt_pk_bf16_f32 v6, v6, v7
	ds_read2_b32 v[8:9], v12 offset0:74 offset1:107
	s_waitcnt lgkmcnt(0)
	v_cvt_pk_bf16_f32 v7, v8, v9
	ds_read2_b32 v[8:9], v12 offset0:140 offset1:173
	s_waitcnt lgkmcnt(0)
	v_cvt_pk_bf16_f32 v8, v8, v9
	ds_read2_b32 v[40:41], v12 offset0:206 offset1:239
	s_waitcnt lgkmcnt(0)
	v_cvt_pk_bf16_f32 v9, v40, v41
	v_lshlrev_b32_e32 v40, 11, v3
	v_mov_b32_e32 v41, v16
	v_lshl_add_u64 v[40:41], v[38:39], 0, v[40:41]
	global_store_dwordx4 v[40:41], v[6:9], off
	ds_read2_b32 v[6:7], v12 offset0:16 offset1:49
	v_or_b32_e32 v3, s0, v14
	s_waitcnt lgkmcnt(0)
	v_cvt_pk_bf16_f32 v6, v6, v7
	ds_read2_b32 v[8:9], v12 offset0:82 offset1:115
	s_waitcnt lgkmcnt(0)
	v_cvt_pk_bf16_f32 v7, v8, v9
	ds_read2_b32 v[8:9], v12 offset0:148 offset1:181
	s_waitcnt lgkmcnt(0)
	v_cvt_pk_bf16_f32 v8, v8, v9
	ds_read2_b32 v[40:41], v12 offset0:214 offset1:247
	s_waitcnt lgkmcnt(0)
	v_cvt_pk_bf16_f32 v9, v40, v41
	v_lshlrev_b32_e32 v40, 11, v3
	v_mov_b32_e32 v41, v16
	v_lshl_add_u64 v[40:41], v[38:39], 0, v[40:41]
	global_store_dwordx4 v[40:41], v[6:9], off
	ds_read2_b32 v[6:7], v12 offset0:24 offset1:57
	v_or_b32_e32 v3, s0, v15
	s_waitcnt lgkmcnt(0)
	v_cvt_pk_bf16_f32 v6, v6, v7
	ds_read2_b32 v[8:9], v12 offset0:90 offset1:123
	s_waitcnt lgkmcnt(0)
	v_cvt_pk_bf16_f32 v7, v8, v9
	ds_read2_b32 v[8:9], v12 offset0:156 offset1:189
	s_waitcnt lgkmcnt(0)
	v_cvt_pk_bf16_f32 v8, v8, v9
	ds_read2_b32 v[40:41], v12 offset0:222 offset1:255
	s_waitcnt lgkmcnt(0)
	v_cvt_pk_bf16_f32 v9, v40, v41
	v_lshlrev_b32_e32 v40, 11, v3
	v_mov_b32_e32 v41, v16
	v_lshl_add_u64 v[38:39], v[38:39], 0, v[40:41]
	global_store_dwordx4 v[38:39], v[6:9], off
	s_waitcnt lgkmcnt(0)
	v_readlane_b32 s76, v252, 9
	v_readlane_b32 s77, v252, 10
	v_readlane_b32 s78, v252, 11
	v_readlane_b32 s79, v252, 12
	v_readlane_b32 s80, v252, 13
	v_readlane_b32 s81, v252, 14
	v_readlane_b32 s82, v252, 15
	v_readlane_b32 s83, v252, 16

.LBB0_159:
	s_andn2_b64 vcc, exec, s[0:1]
	s_cbranch_vccnz .LBB0_185
	s_mul_i32 s1, s2, 0xb00000
	v_readlane_b32 s20, v252, 36
	s_mul_hi_i32 s0, s2, 0xb00000
	v_readlane_b32 s21, v252, 37
	s_add_u32 s3, s20, s1
	s_addc_u32 s17, s21, s0
	s_lshl_b32 s0, s2, 10
	s_ashr_i32 s1, s0, 31
	v_readlane_b32 s68, v251, 52
	s_lshl_b64 s[0:1], s[0:1], 2
	v_readlane_b32 s74, v251, 58
	v_readlane_b32 s75, v251, 59
	s_add_u32 s20, s74, s0
	s_mul_i32 s0, s15, 0xba3
	s_addc_u32 s21, s75, s1
	s_lshr_b32 s1, s0, 31
	s_ashr_i32 s0, s0, 18
	s_add_i32 s0, s0, s1
	s_mul_i32 s1, s0, 0x58
	s_sub_i32 s1, s15, s1
	s_sext_i32_i16 s1, s1
	s_lshl_b32 s4, s1, 5
	s_ashr_i32 s5, s4, 31
	s_lshl_b32 s18, s0, 6
	s_lshl_b64 s[0:1], s[4:5], 2
	s_add_u32 s0, s3, s0
	v_or_b32_e32 v6, s18, v0
	s_addc_u32 s1, s17, s1
	v_mov_b32_e32 v3, v16
	v_lshl_add_u64 v[8:9], s[0:1], 0, v[2:3]
	v_mul_hi_i32_i24_e32 v39, 0x2c00, v6
	v_mul_i32_i24_e32 v38, 0x2c00, v6
	v_lshl_add_u64 v[38:39], v[8:9], 0, v[38:39]
	global_load_dword v62, v[38:39], off nt
	v_mul_i32_i24_e32 v38, 0xb00, v6
	v_ashrrev_i32_e32 v39, 31, v38
	v_lshl_add_u64 v[8:9], v[38:39], 2, v[8:9]
	s_movk_i32 s0, 0x5000
	v_add_co_u32_e32 v38, vcc, s0, v8
	s_mov_b32 s0, 0xb000
	s_nop 0
	v_addc_co_u32_e32 v39, vcc, 0, v9, vcc
	global_load_dword v63, v[38:39], off offset:2048 nt
	v_add_co_u32_e32 v38, vcc, s0, v8
	s_mov_b32 s0, 0x16000
	s_nop 0
	v_addc_co_u32_e32 v39, vcc, 0, v9, vcc
	global_load_dword v64, v[38:39], off nt
	v_add_co_u32_e32 v38, vcc, s11, v8
	v_cndmask_b32_e64 v7, 0, 1, s[50:51]
	s_nop 0
	v_addc_co_u32_e32 v39, vcc, 0, v9, vcc
	global_load_dword v65, v[38:39], off offset:2048 nt
	v_add_co_u32_e32 v38, vcc, s0, v8
	s_mov_b32 s0, 0x1b000
	s_nop 0
	v_addc_co_u32_e32 v39, vcc, 0, v9, vcc
	global_load_dword v58, v[38:39], off nt
	v_add_co_u32_e32 v38, vcc, s0, v8
	s_mov_b32 s0, 0x21000
	s_nop 0
	v_addc_co_u32_e32 v39, vcc, 0, v9, vcc
	global_load_dword v59, v[38:39], off offset:2048 nt
	v_add_co_u32_e32 v38, vcc, s0, v8
	s_mov_b32 s0, 0x26000
	s_nop 0
	v_addc_co_u32_e32 v39, vcc, 0, v9, vcc
	global_load_dword v60, v[38:39], off nt
	v_add_co_u32_e32 v38, vcc, s0, v8
	s_mov_b32 s0, 0x31000
	s_nop 0
	v_addc_co_u32_e32 v39, vcc, 0, v9, vcc
	global_load_dword v61, v[38:39], off offset:2048 nt
	v_add_co_u32_e32 v38, vcc, s12, v8
	v_readlane_b32 s22, v252, 38
	s_nop 0
	v_addc_co_u32_e32 v39, vcc, 0, v9, vcc
	global_load_dword v54, v[38:39], off nt
	v_add_co_u32_e32 v38, vcc, s0, v8
	s_mov_b32 s0, 0x37000
	s_nop 0
	v_addc_co_u32_e32 v39, vcc, 0, v9, vcc
	global_load_dword v55, v[38:39], off offset:2048 nt
	v_add_co_u32_e32 v38, vcc, s0, v8
	s_mov_b32 s0, 0x3c000
	s_nop 0
	v_addc_co_u32_e32 v39, vcc, 0, v9, vcc
	global_load_dword v56, v[38:39], off nt
	v_add_co_u32_e32 v38, vcc, s0, v8
	s_mov_b32 s0, 0x42000
	s_nop 0
	v_addc_co_u32_e32 v39, vcc, 0, v9, vcc
	global_load_dword v57, v[38:39], off offset:2048 nt
	v_add_co_u32_e32 v38, vcc, s0, v8
	s_mov_b32 s0, 0x47000
	s_nop 0
	v_addc_co_u32_e32 v39, vcc, 0, v9, vcc
	global_load_dword v50, v[38:39], off nt
	v_add_co_u32_e32 v38, vcc, s0, v8
	s_mov_b32 s0, 0x4d000
	s_nop 0
	v_addc_co_u32_e32 v39, vcc, 0, v9, vcc
	global_load_dword v51, v[38:39], off offset:2048 nt
	v_add_co_u32_e32 v38, vcc, s0, v8
	s_mov_b32 s0, 0x52000
	s_nop 0
	v_addc_co_u32_e32 v39, vcc, 0, v9, vcc
	global_load_dword v52, v[38:39], off nt
	v_add_co_u32_e32 v38, vcc, s0, v8
	s_mov_b32 s0, 0x58000
	s_nop 0
	v_addc_co_u32_e32 v39, vcc, 0, v9, vcc
	global_load_dword v53, v[38:39], off offset:2048 nt
	v_add_co_u32_e32 v38, vcc, s0, v8
	s_mov_b32 s0, 0x5d000
	s_nop 0
	v_addc_co_u32_e32 v39, vcc, 0, v9, vcc
	global_load_dword v46, v[38:39], off nt
	v_add_co_u32_e32 v38, vcc, s0, v8
	s_mov_b32 s0, 0x63000
	s_nop 0
	v_addc_co_u32_e32 v39, vcc, 0, v9, vcc
	global_load_dword v47, v[38:39], off offset:2048 nt
	v_add_co_u32_e32 v38, vcc, s0, v8
	s_mov_b32 s0, 0x68000
	s_nop 0
	v_addc_co_u32_e32 v39, vcc, 0, v9, vcc
	global_load_dword v48, v[38:39], off nt
	v_add_co_u32_e32 v38, vcc, s0, v8
	s_mov_b32 s0, 0x6e000
	s_nop 0
	v_addc_co_u32_e32 v39, vcc, 0, v9, vcc
	global_load_dword v49, v[38:39], off offset:2048 nt
	v_add_co_u32_e32 v38, vcc, s0, v8
	s_mov_b32 s0, 0x73000
	s_nop 0
	v_addc_co_u32_e32 v39, vcc, 0, v9, vcc
	global_load_dword v42, v[38:39], off nt
	v_add_co_u32_e32 v38, vcc, s0, v8
	s_mov_b32 s0, 0x79000
	s_nop 0
	v_addc_co_u32_e32 v39, vcc, 0, v9, vcc
	global_load_dword v43, v[38:39], off offset:2048 nt
	v_add_co_u32_e32 v38, vcc, s0, v8
	s_mov_b32 s0, 0x7e000
	s_nop 0
	v_addc_co_u32_e32 v39, vcc, 0, v9, vcc
	global_load_dword v44, v[38:39], off nt
	v_add_co_u32_e32 v38, vcc, s0, v8
	s_mov_b32 s0, 0x84000
	s_nop 0
	v_addc_co_u32_e32 v39, vcc, 0, v9, vcc
	global_load_dword v45, v[38:39], off offset:2048 nt
	v_add_co_u32_e32 v38, vcc, s0, v8
	s_mov_b32 s0, 0x89000
	s_nop 0
	v_addc_co_u32_e32 v39, vcc, 0, v9, vcc
	v_add_co_u32_e32 v40, vcc, s0, v8
	s_mov_b32 s0, 0x8f000
	s_nop 0
	v_addc_co_u32_e32 v41, vcc, 0, v9, vcc
	global_load_dword v38, v[38:39], off nt
	v_readlane_b32 s23, v252, 39
	global_load_dword v39, v[40:41], off offset:2048 nt
	v_add_co_u32_e32 v40, vcc, s0, v8
	s_mov_b32 s0, 0x94000
	s_nop 0
	v_addc_co_u32_e32 v41, vcc, 0, v9, vcc
	v_add_co_u32_e32 v66, vcc, s0, v8
	s_mov_b32 s0, 0x9a000
	s_nop 0
	v_addc_co_u32_e32 v67, vcc, 0, v9, vcc
	global_load_dword v40, v[40:41], off nt
	v_readlane_b32 s69, v251, 53
	global_load_dword v41, v[66:67], off offset:2048 nt
	v_add_co_u32_e32 v66, vcc, s0, v8
	v_cmp_ne_u32_e64 s[0:1], 1, v7
	s_nop 0
	v_addc_co_u32_e32 v67, vcc, 0, v9, vcc
	global_load_dword v3, v[66:67], off nt
	v_add_co_u32_e32 v66, vcc, 0x9f000, v8
	v_readlane_b32 s70, v251, 54
	s_nop 0
	v_addc_co_u32_e32 v67, vcc, 0, v9, vcc
	global_load_dword v5, v[66:67], off offset:2048 nt
	v_add_co_u32_e32 v66, vcc, 0xa5000, v8
	v_readlane_b32 s71, v251, 55
	s_nop 0
	v_addc_co_u32_e32 v67, vcc, 0, v9, vcc
	v_add_co_u32_e32 v8, vcc, 0xaa000, v8
	global_load_dword v37, v[66:67], off nt
	s_nop 0
	v_addc_co_u32_e32 v9, vcc, 0, v9, vcc
	global_load_dword v8, v[8:9], off offset:2048 nt
	s_andn2_b64 vcc, exec, s[50:51]
	v_add_u32_e32 v9, v10, v18
	v_readlane_b32 s72, v251, 56
	v_readlane_b32 s73, v251, 57
	s_cbranch_vccnz .LBB0_189
	v_ashrrev_i32_e32 v7, 31, v6
	v_lshl_add_u64 v[6:7], v[6:7], 2, s[20:21]
	global_load_dword v6, v[6:7], off nt
	s_ashr_i32 s19, s18, 31
	s_waitcnt vmcnt(0)
	v_mul_f32_e32 v68, v62, v6
	v_lshl_add_u64 v[6:7], s[18:19], 0, v[0:1]
	v_lshl_add_u64 v[66:67], v[6:7], 2, s[20:21]
	global_load_dword v6, v[66:67], off offset:8 nt
	global_load_dword v7, v[66:67], off offset:24 nt
	ds_write_b32 v29, v68
	s_waitcnt vmcnt(1)
	v_mul_f32_e32 v6, v63, v6
	ds_write_b32 v9, v6
	global_load_dword v6, v[66:67], off offset:16 nt
	s_waitcnt vmcnt(0)
	v_mul_f32_e32 v6, v64, v6
	s_cbranch_execnz .LBB0_163

.LBB0_163:
	v_add_u32_e32 v9, v10, v19
	s_waitcnt vmcnt(28)
	v_mul_f32_e32 v7, v65, v7
	ds_write2_b32 v9, v6, v7 offset1:66
	s_and_b64 vcc, exec, s[0:1]
	v_add_u32_e32 v6, v10, v20
	s_cbranch_vccnz .LBB0_190
	s_ashr_i32 s19, s18, 31
	v_lshl_add_u64 v[62:63], s[18:19], 0, v[0:1]
	v_lshl_add_u64 v[62:63], v[62:63], 2, s[20:21]
	global_load_dword v7, v[62:63], off offset:32 nt
	global_load_dword v9, v[62:63], off offset:40 nt
	s_waitcnt vmcnt(1)
	v_mul_f32_e32 v7, v58, v7
	s_waitcnt vmcnt(0)
	v_mul_f32_e32 v9, v59, v9
	ds_write2_b32 v6, v7, v9 offset1:66
	global_load_dword v7, v[62:63], off offset:48 nt
	global_load_dword v9, v[62:63], off offset:56 nt
	s_waitcnt vmcnt(1)
	v_mul_f32_e32 v7, v60, v7
	s_cbranch_execnz .LBB0_166

.LBB0_166:
	v_add_u32_e32 v6, v10, v21
	s_waitcnt vmcnt(0)
	v_mul_f32_e32 v9, v61, v9
	ds_write2_b32 v6, v7, v9 offset1:66
	s_and_b64 vcc, exec, s[0:1]
	v_add_u32_e32 v6, v10, v22
	s_cbranch_vccnz .LBB0_191
	s_ashr_i32 s19, s18, 31
	v_lshl_add_u64 v[58:59], s[18:19], 0, v[0:1]
	v_lshl_add_u64 v[58:59], v[58:59], 2, s[20:21]
	global_load_dword v7, v[58:59], off offset:64 nt
	global_load_dword v9, v[58:59], off offset:72 nt
	s_waitcnt vmcnt(1)
	v_mul_f32_e32 v7, v54, v7
	s_waitcnt vmcnt(0)
	v_mul_f32_e32 v9, v55, v9
	ds_write2_b32 v6, v7, v9 offset1:66
	global_load_dword v7, v[58:59], off offset:80 nt
	global_load_dword v9, v[58:59], off offset:88 nt
	s_waitcnt vmcnt(1)
	v_mul_f32_e32 v7, v56, v7
	s_cbranch_execnz .LBB0_169

.LBB0_169:
	v_add_u32_e32 v6, v10, v23
	s_waitcnt vmcnt(0)
	v_mul_f32_e32 v9, v57, v9
	ds_write2_b32 v6, v7, v9 offset1:66
	s_and_b64 vcc, exec, s[0:1]
	v_add_u32_e32 v6, v10, v24
	s_cbranch_vccnz .LBB0_192
	s_ashr_i32 s19, s18, 31
	v_lshl_add_u64 v[54:55], s[18:19], 0, v[0:1]
	v_lshl_add_u64 v[54:55], v[54:55], 2, s[20:21]
	global_load_dword v7, v[54:55], off offset:96 nt
	global_load_dword v9, v[54:55], off offset:104 nt
	s_waitcnt vmcnt(1)
	v_mul_f32_e32 v7, v50, v7
	s_waitcnt vmcnt(0)
	v_mul_f32_e32 v9, v51, v9
	ds_write2_b32 v6, v7, v9 offset1:66
	global_load_dword v7, v[54:55], off offset:112 nt
	global_load_dword v9, v[54:55], off offset:120 nt
	s_waitcnt vmcnt(1)
	v_mul_f32_e32 v7, v52, v7
	s_cbranch_execnz .LBB0_172

.LBB0_172:
	v_add_u32_e32 v6, v10, v25
	s_waitcnt vmcnt(0)
	v_mul_f32_e32 v9, v53, v9
	ds_write2_b32 v6, v7, v9 offset1:66
	s_and_b64 vcc, exec, s[0:1]
	v_add_u32_e32 v6, v10, v26
	s_cbranch_vccnz .LBB0_193
	s_ashr_i32 s19, s18, 31
	v_lshl_add_u64 v[50:51], s[18:19], 0, v[0:1]
	v_lshl_add_u64 v[50:51], v[50:51], 2, s[20:21]
	global_load_dword v7, v[50:51], off offset:128 nt
	global_load_dword v9, v[50:51], off offset:136 nt
	s_waitcnt vmcnt(1)
	v_mul_f32_e32 v7, v46, v7
	s_waitcnt vmcnt(0)
	v_mul_f32_e32 v9, v47, v9
	ds_write2_b32 v6, v7, v9 offset1:66
	global_load_dword v7, v[50:51], off offset:144 nt
	global_load_dword v9, v[50:51], off offset:152 nt
	s_waitcnt vmcnt(1)
	v_mul_f32_e32 v7, v48, v7
	s_cbranch_execnz .LBB0_175

.LBB0_175:
	v_add_u32_e32 v6, v10, v27
	s_waitcnt vmcnt(0)
	v_mul_f32_e32 v9, v49, v9
	ds_write2_b32 v6, v7, v9 offset1:66
	s_and_b64 vcc, exec, s[0:1]
	v_add_u32_e32 v6, v10, v28
	s_cbranch_vccnz .LBB0_194
	s_ashr_i32 s19, s18, 31
	v_lshl_add_u64 v[46:47], s[18:19], 0, v[0:1]
	v_lshl_add_u64 v[46:47], v[46:47], 2, s[20:21]
	global_load_dword v7, v[46:47], off offset:160 nt
	global_load_dword v9, v[46:47], off offset:168 nt
	s_waitcnt vmcnt(1)
	v_mul_f32_e32 v7, v42, v7
	s_waitcnt vmcnt(0)
	v_mul_f32_e32 v9, v43, v9
	ds_write2_b32 v6, v7, v9 offset1:66
	global_load_dword v7, v[46:47], off offset:176 nt
	global_load_dword v9, v[46:47], off offset:184 nt
	s_waitcnt vmcnt(1)
	v_mul_f32_e32 v7, v44, v7
	s_cbranch_execnz .LBB0_178

.LBB0_178:
	s_waitcnt vmcnt(0)
	v_mul_f32_e32 v9, v45, v9
	ds_write2_b32 v6, v7, v9 offset0:132 offset1:198
	s_and_b64 vcc, exec, s[0:1]
	v_add_u32_e32 v7, 0x400, v6
	s_cbranch_vccnz .LBB0_195
	s_ashr_i32 s19, s18, 31
	v_lshl_add_u64 v[42:43], s[18:19], 0, v[0:1]
	v_lshl_add_u64 v[42:43], v[42:43], 2, s[20:21]
	global_load_dword v9, v[42:43], off offset:192 nt
	global_load_dword v44, v[42:43], off offset:200 nt
	s_waitcnt vmcnt(1)
	v_mul_f32_e32 v9, v38, v9
	s_waitcnt vmcnt(0)
	v_mul_f32_e32 v44, v39, v44
	ds_write2_b32 v7, v9, v44 offset0:8 offset1:74
	global_load_dword v9, v[42:43], off offset:208 nt
	s_waitcnt vmcnt(0)
	v_mul_f32_e32 v9, v40, v9
	global_load_dword v42, v[42:43], off offset:216 nt
	s_cbranch_execnz .LBB0_181

.LBB0_181:
	s_waitcnt vmcnt(0)
	v_mul_f32_e32 v38, v41, v42
	s_and_b64 vcc, exec, s[0:1]
	v_add_u32_e32 v6, 0x800, v6
	ds_write2_b32 v7, v9, v38 offset0:140 offset1:206
	s_cbranch_vccnz .LBB0_196
	s_ashr_i32 s19, s18, 31
	v_lshl_add_u64 v[38:39], s[18:19], 0, v[0:1]
	v_lshl_add_u64 v[38:39], v[38:39], 2, s[20:21]
	global_load_dword v7, v[38:39], off offset:224 nt
	global_load_dword v9, v[38:39], off offset:232 nt
	s_waitcnt vmcnt(1)
	v_mul_f32_e32 v7, v3, v7
	s_waitcnt vmcnt(0)
	v_mul_f32_e32 v9, v5, v9
	ds_write2_b32 v6, v7, v9 offset0:16 offset1:82
	global_load_dword v7, v[38:39], off offset:240 nt
	global_load_dword v9, v[38:39], off offset:248 nt
	s_waitcnt vmcnt(1)
	v_mul_f32_e32 v7, v37, v7
	s_cbranch_execnz .LBB0_184

.LBB0_895:
	v_readlane_b32 s0, v253, 26
	s_cmp_ge_i32 s12, s0
	v_readlane_b32 s0, v253, 36
	s_cselect_b32 s0, s0, 0
	s_add_i32 s0, s0, s12
	v_readlane_b32 s1, v253, 24
	s_cmp_ge_i32 s0, s1
	s_mov_b32 s6, 2
	s_cbranch_scc1 .LBB0_956
	s_mul_hi_i32 s1, s0, 0xae4c415d
	s_add_i32 s1, s1, s0
	s_lshr_b32 s2, s1, 31
	s_ashr_i32 s1, s1, 12
	s_add_i32 s2, s1, s2
	s_mul_i32 s1, s2, 0x1780
	s_sub_i32 s10, s0, s1
	s_ashr_i32 s3, s2, 31
	s_cmpk_gt_i32 s10, 0x57f
	s_mov_b64 s[0:1], -1
	s_cbranch_scc0 .LBB0_930
	s_cmpk_gt_u32 s10, 0x77f
	s_cbranch_scc0 .LBB0_927
	s_lshl_b64 s[0:1], s[2:3], 24
	s_lshl_b64 s[4:5], s[2:3], 23
	s_cmpk_gt_u32 s10, 0xf7f
	s_mov_b64 s[6:7], -1
	s_cbranch_scc0 .LBB0_900
	v_readlane_b32 s16, v252, 1
	v_readlane_b32 s24, v252, 9
	v_readlane_b32 s25, v252, 10
	s_add_u32 s11, s24, s0
	s_addc_u32 s13, s25, s1
	v_readlane_b32 s6, v248, 38
	s_add_u32 s7, s6, s4
	v_readlane_b32 s6, v248, 39
	s_addc_u32 s8, s6, s5
	s_lshl_b32 s6, s10, 1
	s_add_i32 s6, s6, 0x1e100
	s_and_b32 s9, s6, 0x1ffc0
	s_lshl_b32 s6, s10, 5
	s_and_b32 s6, s6, 0x3e0
	s_lshl_b32 s14, s6, 2
	s_add_u32 s14, s11, s14
	v_or_b32_e32 v8, s9, v0
	s_addc_u32 s15, s13, 0
	v_lshlrev_b32_e32 v6, 2, v2
	v_mov_b32_e32 v7, v16
	v_lshl_add_u64 v[6:7], s[14:15], 0, v[6:7]
	v_lshlrev_b32_e32 v8, 12, v8
	v_mov_b32_e32 v9, v16
	v_lshl_add_u64 v[6:7], v[6:7], 0, v[8:9]
	s_movk_i32 s11, 0x2000
	v_add_co_u32_e32 v8, vcc, s11, v6
	s_movk_i32 s11, 0x4000
	s_nop 0
	v_addc_co_u32_e32 v9, vcc, 0, v7, vcc
	global_load_dword v28, v[6:7], off nt
	global_load_dword v29, v[8:9], off nt
	v_add_co_u32_e32 v8, vcc, s11, v6
	s_movk_i32 s11, 0x6000
	s_nop 0
	v_addc_co_u32_e32 v9, vcc, 0, v7, vcc
	global_load_dword v30, v[8:9], off nt
	v_add_co_u32_e32 v8, vcc, s11, v6
	s_mov_b32 s11, 0x8000
	s_nop 0
	v_addc_co_u32_e32 v9, vcc, 0, v7, vcc
	global_load_dword v31, v[8:9], off nt
	v_add_co_u32_e32 v8, vcc, s11, v6
	s_mov_b32 s11, 0xa000
	s_nop 0
	v_addc_co_u32_e32 v9, vcc, 0, v7, vcc
	global_load_dword v32, v[8:9], off nt
	v_add_co_u32_e32 v8, vcc, s11, v6
	s_mov_b32 s11, 0xc000
	s_nop 0
	v_addc_co_u32_e32 v9, vcc, 0, v7, vcc
	global_load_dword v33, v[8:9], off nt
	v_add_co_u32_e32 v8, vcc, s11, v6
	s_mov_b32 s11, 0xe000
	s_nop 0
	v_addc_co_u32_e32 v9, vcc, 0, v7, vcc
	global_load_dword v34, v[8:9], off nt
	v_add_co_u32_e32 v8, vcc, s11, v6
	s_mov_b32 s11, 0x10000
	s_nop 0
	v_addc_co_u32_e32 v9, vcc, 0, v7, vcc
	global_load_dword v35, v[8:9], off nt
	v_add_co_u32_e32 v8, vcc, s11, v6
	s_mov_b32 s11, 0x12000
	s_nop 0
	v_addc_co_u32_e32 v9, vcc, 0, v7, vcc
	global_load_dword v36, v[8:9], off nt
	v_add_co_u32_e32 v8, vcc, s11, v6
	s_mov_b32 s11, 0x14000
	s_nop 0
	v_addc_co_u32_e32 v9, vcc, 0, v7, vcc
	global_load_dword v37, v[8:9], off nt
	v_add_co_u32_e32 v8, vcc, s11, v6
	s_mov_b32 s11, 0x16000
	s_nop 0
	v_addc_co_u32_e32 v9, vcc, 0, v7, vcc
	global_load_dword v38, v[8:9], off nt
	v_add_co_u32_e32 v8, vcc, s11, v6
	s_mov_b32 s11, 0x18000
	s_nop 0
	v_addc_co_u32_e32 v9, vcc, 0, v7, vcc
	global_load_dword v39, v[8:9], off nt
	v_add_co_u32_e32 v8, vcc, s11, v6
	s_mov_b32 s11, 0x1a000
	s_nop 0
	v_addc_co_u32_e32 v9, vcc, 0, v7, vcc
	global_load_dword v40, v[8:9], off nt
	v_add_co_u32_e32 v8, vcc, s11, v6
	s_mov_b32 s11, 0x1c000
	s_nop 0
	v_addc_co_u32_e32 v9, vcc, 0, v7, vcc
	global_load_dword v41, v[8:9], off nt
	v_add_co_u32_e32 v8, vcc, s11, v6
	s_mov_b32 s11, 0x1e000
	s_nop 0
	v_addc_co_u32_e32 v9, vcc, 0, v7, vcc
	global_load_dword v42, v[8:9], off nt
	v_add_co_u32_e32 v8, vcc, s11, v6
	s_mov_b32 s11, 0x20000
	s_nop 0
	v_addc_co_u32_e32 v9, vcc, 0, v7, vcc
	global_load_dword v43, v[8:9], off nt
	v_add_co_u32_e32 v8, vcc, s11, v6
	s_mov_b32 s11, 0x22000
	s_nop 0
	v_addc_co_u32_e32 v9, vcc, 0, v7, vcc
	global_load_dword v44, v[8:9], off nt
	v_add_co_u32_e32 v8, vcc, s11, v6
	s_mov_b32 s11, 0x24000
	s_nop 0
	v_addc_co_u32_e32 v9, vcc, 0, v7, vcc
	global_load_dword v45, v[8:9], off nt
	v_add_co_u32_e32 v8, vcc, s11, v6
	s_mov_b32 s11, 0x26000
	s_nop 0
	v_addc_co_u32_e32 v9, vcc, 0, v7, vcc
	global_load_dword v46, v[8:9], off nt
	v_add_co_u32_e32 v8, vcc, s11, v6
	s_mov_b32 s11, 0x28000
	s_nop 0
	v_addc_co_u32_e32 v9, vcc, 0, v7, vcc
	global_load_dword v47, v[8:9], off nt
	v_add_co_u32_e32 v8, vcc, s11, v6
	s_mov_b32 s11, 0x2a000
	s_nop 0
	v_addc_co_u32_e32 v9, vcc, 0, v7, vcc
	global_load_dword v48, v[8:9], off nt
	v_add_co_u32_e32 v8, vcc, s11, v6
	s_mov_b32 s11, 0x2e000
	s_nop 0
	v_addc_co_u32_e32 v9, vcc, 0, v7, vcc
	global_load_dword v49, v[8:9], off nt
	v_add_co_u32_e32 v8, vcc, s44, v6
	s_lshl_b32 s9, s9, 1
	s_nop 0
	v_addc_co_u32_e32 v9, vcc, 0, v7, vcc
	global_load_dword v50, v[8:9], off nt
	v_add_co_u32_e32 v8, vcc, s11, v6
	s_mov_b32 s11, 0x30000
	s_nop 0
	v_addc_co_u32_e32 v9, vcc, 0, v7, vcc
	global_load_dword v51, v[8:9], off nt
	v_add_co_u32_e32 v8, vcc, s11, v6
	s_mov_b32 s11, 0x32000
	s_nop 0
	v_addc_co_u32_e32 v9, vcc, 0, v7, vcc
	global_load_dword v52, v[8:9], off nt
	v_add_co_u32_e32 v8, vcc, s11, v6
	s_mov_b32 s11, 0x34000
	s_nop 0
	v_addc_co_u32_e32 v9, vcc, 0, v7, vcc
	global_load_dword v53, v[8:9], off nt
	v_add_co_u32_e32 v8, vcc, s11, v6
	s_mov_b32 s11, 0x36000
	s_nop 0
	v_addc_co_u32_e32 v9, vcc, 0, v7, vcc
	global_load_dword v54, v[8:9], off nt
	v_add_co_u32_e32 v8, vcc, s11, v6
	s_mov_b32 s11, 0x38000
	s_nop 0
	v_addc_co_u32_e32 v9, vcc, 0, v7, vcc
	global_load_dword v55, v[8:9], off nt
	v_add_co_u32_e32 v8, vcc, s11, v6
	s_mov_b32 s11, 0x3a000
	s_nop 0
	v_addc_co_u32_e32 v9, vcc, 0, v7, vcc
	global_load_dword v56, v[8:9], off nt
	v_add_co_u32_e32 v8, vcc, s11, v6
	s_mov_b32 s11, 0x3c000
	s_nop 0
	v_addc_co_u32_e32 v9, vcc, 0, v7, vcc
	global_load_dword v57, v[8:9], off nt
	v_add_co_u32_e32 v8, vcc, s11, v6
	s_mov_b32 s11, 0x3e000
	s_nop 0
	v_addc_co_u32_e32 v9, vcc, 0, v7, vcc
	v_add_co_u32_e32 v6, vcc, s11, v6
	global_load_dword v8, v[8:9], off nt
	s_nop 0
	v_addc_co_u32_e32 v7, vcc, 0, v7, vcc
	global_load_dword v6, v[6:7], off nt
	v_add_u32_e32 v7, v5, v10
	v_add_u32_e32 v9, 0x400, v7
	s_waitcnt vmcnt(30)
	ds_write2_b32 v7, v28, v29 offset1:66
	s_waitcnt vmcnt(28)
	ds_write2_b32 v7, v30, v31 offset0:132 offset1:198
	s_waitcnt vmcnt(26)
	ds_write2_b32 v9, v32, v33 offset0:8 offset1:74
	s_waitcnt vmcnt(24)
	ds_write2_b32 v9, v34, v35 offset0:140 offset1:206
	v_add_u32_e32 v9, 0x800, v7
	s_waitcnt vmcnt(22)
	ds_write2_b32 v9, v36, v37 offset0:16 offset1:82
	s_waitcnt vmcnt(20)
	ds_write2_b32 v9, v38, v39 offset0:148 offset1:214
	v_add_u32_e32 v9, 0xc00, v7
	s_waitcnt vmcnt(18)
	ds_write2_b32 v9, v40, v41 offset0:24 offset1:90
	s_waitcnt vmcnt(16)
	ds_write2_b32 v9, v42, v43 offset0:156 offset1:222
	v_add_u32_e32 v9, 0x1000, v7
	s_waitcnt vmcnt(14)
	ds_write2_b32 v9, v44, v45 offset0:32 offset1:98
	s_waitcnt vmcnt(12)
	ds_write2_b32 v9, v46, v47 offset0:164 offset1:230
	v_add_u32_e32 v9, 0x1400, v7
	s_waitcnt vmcnt(10)
	ds_write2_b32 v9, v48, v49 offset0:40 offset1:106
	s_waitcnt vmcnt(8)
	ds_write2_b32 v9, v50, v51 offset0:172 offset1:238
	v_add_u32_e32 v9, 0x1800, v7
	v_add_u32_e32 v7, 0x1c00, v7
	s_waitcnt vmcnt(6)
	ds_write2_b32 v9, v52, v53 offset0:48 offset1:114
	s_waitcnt vmcnt(4)
	ds_write2_b32 v9, v54, v55 offset0:180 offset1:246
	s_waitcnt vmcnt(2)
	ds_write2_b32 v7, v56, v57 offset0:56 offset1:122
	s_waitcnt vmcnt(0)
	ds_write2_b32 v7, v8, v6 offset0:188 offset1:254
	s_waitcnt lgkmcnt(0)
	ds_read2_b32 v[8:9], v12 offset1:33
	s_waitcnt lgkmcnt(0)
	v_cvt_pk_bf16_f32 v28, v8, v9
	ds_read2_b32 v[8:9], v12 offset0:66 offset1:99
	s_waitcnt lgkmcnt(0)
	v_cvt_pk_bf16_f32 v29, v8, v9
	ds_read2_b32 v[8:9], v12 offset0:132 offset1:165
	s_add_u32 s14, s7, s9
	s_waitcnt lgkmcnt(0)
	v_cvt_pk_bf16_f32 v30, v8, v9
	ds_read2_b32 v[8:9], v12 offset0:198 offset1:231
	s_addc_u32 s15, s8, 0
	v_lshlrev_b32_e32 v6, 1, v4
	v_mov_b32_e32 v7, v16
	s_waitcnt lgkmcnt(0)
	v_cvt_pk_bf16_f32 v31, v8, v9
	v_or_b32_e32 v8, s6, v11
	v_lshl_add_u64 v[6:7], s[14:15], 0, v[6:7]
	v_lshlrev_b32_e32 v8, 13, v8
	v_mov_b32_e32 v9, v16
	v_lshl_add_u64 v[8:9], v[6:7], 0, v[8:9]
	global_store_dwordx4 v[8:9], v[28:31], off
	ds_read2_b32 v[8:9], v12 offset0:8 offset1:41
	v_readlane_b32 s17, v252, 2
	s_waitcnt lgkmcnt(0)
	v_cvt_pk_bf16_f32 v28, v8, v9
	ds_read2_b32 v[8:9], v12 offset0:74 offset1:107
	s_waitcnt lgkmcnt(0)
	v_cvt_pk_bf16_f32 v29, v8, v9
	ds_read2_b32 v[8:9], v12 offset0:140 offset1:173
	s_waitcnt lgkmcnt(0)
	v_cvt_pk_bf16_f32 v30, v8, v9
	ds_read2_b32 v[8:9], v12 offset0:206 offset1:239
	s_waitcnt lgkmcnt(0)
	v_cvt_pk_bf16_f32 v31, v8, v9
	v_or_b32_e32 v8, s6, v13
	v_lshlrev_b32_e32 v8, 13, v8
	v_mov_b32_e32 v9, v16
	v_lshl_add_u64 v[8:9], v[6:7], 0, v[8:9]
	global_store_dwordx4 v[8:9], v[28:31], off
	ds_read2_b32 v[8:9], v12 offset0:16 offset1:49
	v_readlane_b32 s18, v252, 3
	s_waitcnt lgkmcnt(0)
	v_cvt_pk_bf16_f32 v28, v8, v9
	ds_read2_b32 v[8:9], v12 offset0:82 offset1:115
	s_waitcnt lgkmcnt(0)
	v_cvt_pk_bf16_f32 v29, v8, v9
	ds_read2_b32 v[8:9], v12 offset0:148 offset1:181
	s_waitcnt lgkmcnt(0)
	v_cvt_pk_bf16_f32 v30, v8, v9
	ds_read2_b32 v[8:9], v12 offset0:214 offset1:247
	s_waitcnt lgkmcnt(0)
	v_cvt_pk_bf16_f32 v31, v8, v9
	v_or_b32_e32 v8, s6, v14
	v_lshlrev_b32_e32 v8, 13, v8
	v_mov_b32_e32 v9, v16
	v_lshl_add_u64 v[8:9], v[6:7], 0, v[8:9]
	global_store_dwordx4 v[8:9], v[28:31], off
	ds_read2_b32 v[8:9], v12 offset0:24 offset1:57
	v_readlane_b32 s19, v252, 4
	s_waitcnt lgkmcnt(0)
	v_cvt_pk_bf16_f32 v28, v8, v9
	ds_read2_b32 v[8:9], v12 offset0:90 offset1:123
	s_waitcnt lgkmcnt(0)
	v_cvt_pk_bf16_f32 v29, v8, v9
	ds_read2_b32 v[8:9], v12 offset0:156 offset1:189
	s_waitcnt lgkmcnt(0)
	v_cvt_pk_bf16_f32 v30, v8, v9
	ds_read2_b32 v[8:9], v12 offset0:222 offset1:255
	s_waitcnt lgkmcnt(0)
	v_cvt_pk_bf16_f32 v31, v8, v9
	v_or_b32_e32 v8, s6, v15
	v_lshlrev_b32_e32 v8, 13, v8
	v_mov_b32_e32 v9, v16
	v_lshl_add_u64 v[6:7], v[6:7], 0, v[8:9]
	global_store_dwordx4 v[6:7], v[28:31], off
	s_waitcnt lgkmcnt(0)
	v_readlane_b32 s20, v252, 5
	v_readlane_b32 s21, v252, 6
	v_readlane_b32 s22, v252, 7
	v_readlane_b32 s23, v252, 8
	v_readlane_b32 s26, v252, 11
	v_readlane_b32 s27, v252, 12
	v_readlane_b32 s28, v252, 13
	v_readlane_b32 s29, v252, 14
	v_readlane_b32 s30, v252, 15
	v_readlane_b32 s31, v252, 16
	s_mov_b64 s[6:7], 0
.LBB0_900:
	s_andn2_b64 vcc, exec, s[6:7]
	s_mov_b32 s6, 0
	s_cbranch_vccnz .LBB0_926
	v_readlane_b32 s16, v252, 1
	v_readlane_b32 s22, v252, 7
	v_readlane_b32 s23, v252, 8
	s_add_u32 s8, s22, s0
	s_addc_u32 s9, s23, s1
	s_lshl_b32 s0, s2, 10
	s_ashr_i32 s1, s0, 31
	v_readlane_b32 s20, v252, 5
	s_lshl_b64 s[0:1], s[0:1], 2
	v_readlane_b32 s21, v252, 6
	s_add_u32 s6, s20, s0
	s_addc_u32 s7, s21, s1
	s_add_i32 s0, s10, 0xf880
	s_lshr_b32 s0, s0, 1
	s_and_b32 s13, s0, 0x7fc0
	s_lshl_b32 s0, s10, 5
	s_and_b32 s11, s0, 0xfe0
	s_lshl_b32 s0, s11, 2
	s_add_u32 s0, s8, s0
	v_or_b32_e32 v57, s13, v0
	s_addc_u32 s1, s9, 0
	v_lshlrev_b32_e32 v6, 2, v2
	v_mov_b32_e32 v7, v16
	v_lshl_add_u64 v[6:7], s[0:1], 0, v[6:7]
	v_lshlrev_b32_e32 v8, 14, v57
	v_mov_b32_e32 v9, v16
	v_lshl_add_u64 v[6:7], v[6:7], 0, v[8:9]
	s_mov_b32 s0, 0x8000
	v_add_co_u32_e32 v8, vcc, s0, v6
	s_mov_b32 s0, 0x10000
	s_nop 0
	v_addc_co_u32_e32 v9, vcc, 0, v7, vcc
	global_load_dword v53, v[6:7], off nt
	global_load_dword v54, v[8:9], off nt
	v_add_co_u32_e32 v8, vcc, s0, v6
	s_mov_b32 s0, 0x18000
	s_nop 0
	v_addc_co_u32_e32 v9, vcc, 0, v7, vcc
	global_load_dword v55, v[8:9], off nt
	v_add_co_u32_e32 v8, vcc, s0, v6
	s_mov_b32 s0, 0x20000
	s_nop 0
	v_addc_co_u32_e32 v9, vcc, 0, v7, vcc
	global_load_dword v56, v[8:9], off nt
	v_add_co_u32_e32 v8, vcc, s0, v6
	s_mov_b32 s0, 0x28000
	s_nop 0
	v_addc_co_u32_e32 v9, vcc, 0, v7, vcc
	global_load_dword v49, v[8:9], off nt
	v_add_co_u32_e32 v8, vcc, s0, v6
	s_mov_b32 s0, 0x30000
	s_nop 0
	v_addc_co_u32_e32 v9, vcc, 0, v7, vcc
	global_load_dword v50, v[8:9], off nt
	v_add_co_u32_e32 v8, vcc, s0, v6
	s_mov_b32 s0, 0x38000
	s_nop 0
	v_addc_co_u32_e32 v9, vcc, 0, v7, vcc
	global_load_dword v51, v[8:9], off nt
	v_add_co_u32_e32 v8, vcc, s0, v6
	s_mov_b32 s0, 0x40000
	s_nop 0
	v_addc_co_u32_e32 v9, vcc, 0, v7, vcc
	global_load_dword v52, v[8:9], off nt
	v_add_co_u32_e32 v8, vcc, s0, v6
	s_mov_b32 s0, 0x48000
	s_nop 0
	v_addc_co_u32_e32 v9, vcc, 0, v7, vcc
	global_load_dword v45, v[8:9], off nt
	v_add_co_u32_e32 v8, vcc, s0, v6
	s_mov_b32 s0, 0x50000
	s_nop 0
	v_addc_co_u32_e32 v9, vcc, 0, v7, vcc
	global_load_dword v46, v[8:9], off nt
	v_add_co_u32_e32 v8, vcc, s0, v6
	s_mov_b32 s0, 0x58000
	s_nop 0
	v_addc_co_u32_e32 v9, vcc, 0, v7, vcc
	global_load_dword v47, v[8:9], off nt
	v_add_co_u32_e32 v8, vcc, s0, v6
	s_mov_b32 s0, 0x60000
	s_nop 0
	v_addc_co_u32_e32 v9, vcc, 0, v7, vcc
	global_load_dword v48, v[8:9], off nt
	v_add_co_u32_e32 v8, vcc, s0, v6
	s_mov_b32 s0, 0x68000
	s_nop 0
	v_addc_co_u32_e32 v9, vcc, 0, v7, vcc
	global_load_dword v41, v[8:9], off nt
	v_add_co_u32_e32 v8, vcc, s0, v6
	s_mov_b32 s0, 0x70000
	s_nop 0
	v_addc_co_u32_e32 v9, vcc, 0, v7, vcc
	global_load_dword v42, v[8:9], off nt
	v_add_co_u32_e32 v8, vcc, s0, v6
	s_mov_b32 s0, 0x78000
	s_nop 0
	v_addc_co_u32_e32 v9, vcc, 0, v7, vcc
	global_load_dword v43, v[8:9], off nt
	v_add_co_u32_e32 v8, vcc, s0, v6
	s_mov_b32 s0, 0x80000
	s_nop 0
	v_addc_co_u32_e32 v9, vcc, 0, v7, vcc
	global_load_dword v44, v[8:9], off nt
	v_add_co_u32_e32 v8, vcc, s0, v6
	s_mov_b32 s0, 0x88000
	s_nop 0
	v_addc_co_u32_e32 v9, vcc, 0, v7, vcc
	global_load_dword v37, v[8:9], off nt
	v_add_co_u32_e32 v8, vcc, s0, v6
	s_mov_b32 s0, 0x90000
	s_nop 0
	v_addc_co_u32_e32 v9, vcc, 0, v7, vcc
	global_load_dword v38, v[8:9], off nt
	v_add_co_u32_e32 v8, vcc, s0, v6
	s_mov_b32 s0, 0x98000
	s_nop 0
	v_addc_co_u32_e32 v9, vcc, 0, v7, vcc
	global_load_dword v39, v[8:9], off nt
	v_add_co_u32_e32 v8, vcc, s0, v6
	s_mov_b32 s0, 0xa0000
	s_nop 0
	v_addc_co_u32_e32 v9, vcc, 0, v7, vcc
	global_load_dword v40, v[8:9], off nt
	v_add_co_u32_e32 v8, vcc, s0, v6
	s_mov_b32 s0, 0xa8000
	s_nop 0
	v_addc_co_u32_e32 v9, vcc, 0, v7, vcc
	global_load_dword v32, v[8:9], off nt
	v_add_co_u32_e32 v8, vcc, s0, v6
	s_mov_b32 s0, 0xb0000
	s_nop 0
	v_addc_co_u32_e32 v9, vcc, 0, v7, vcc
	global_load_dword v34, v[8:9], off nt
	v_add_co_u32_e32 v8, vcc, s0, v6
	s_mov_b32 s0, 0xb8000
	s_nop 0
	v_addc_co_u32_e32 v9, vcc, 0, v7, vcc
	global_load_dword v35, v[8:9], off nt
	v_add_co_u32_e32 v8, vcc, s0, v6
	s_mov_b32 s0, 0xc0000
	s_nop 0
	v_addc_co_u32_e32 v9, vcc, 0, v7, vcc
	global_load_dword v36, v[8:9], off nt
	v_add_co_u32_e32 v8, vcc, s0, v6
	s_mov_b32 s0, 0xc8000
	s_nop 0
	v_addc_co_u32_e32 v9, vcc, 0, v7, vcc
	global_load_dword v29, v[8:9], off nt
	v_add_co_u32_e32 v8, vcc, s0, v6
	s_mov_b32 s0, 0xd0000
	s_nop 0
	v_addc_co_u32_e32 v9, vcc, 0, v7, vcc
	global_load_dword v30, v[8:9], off nt
	v_add_co_u32_e32 v8, vcc, s0, v6
	s_mov_b32 s0, 0xd8000
	s_nop 0
	v_addc_co_u32_e32 v9, vcc, 0, v7, vcc
	global_load_dword v31, v[8:9], off nt
	v_add_co_u32_e32 v8, vcc, s0, v6
	s_mov_b32 s0, 0xe0000
	s_nop 0
	v_addc_co_u32_e32 v9, vcc, 0, v7, vcc
	global_load_dword v33, v[8:9], off nt
	v_add_co_u32_e32 v8, vcc, s0, v6
	v_readlane_b32 s8, v248, 44
	s_nop 0
	v_addc_co_u32_e32 v9, vcc, 0, v7, vcc
	v_add_co_u32_e32 v58, vcc, 0xe8000, v6
	global_load_dword v8, v[8:9], off nt
	s_nop 0
	v_addc_co_u32_e32 v59, vcc, 0, v7, vcc
	global_load_dword v9, v[58:59], off nt
	v_add_co_u32_e32 v58, vcc, 0xf0000, v6
	v_readlane_b32 s9, v248, 45
	s_nop 0
	v_addc_co_u32_e32 v59, vcc, 0, v7, vcc
	v_add_co_u32_e32 v6, vcc, 0xf8000, v6
	global_load_dword v28, v[58:59], off nt
	s_nop 0
	v_addc_co_u32_e32 v7, vcc, 0, v7, vcc
	global_load_dword v6, v[6:7], off nt
	v_cndmask_b32_e64 v7, 0, 1, s[8:9]
	v_cmp_ne_u32_e64 s[0:1], 1, v7
	s_andn2_b64 vcc, exec, s[8:9]
	v_add_lshl_u32 v7, s13, v0, 2
	v_readlane_b32 s17, v252, 2
	v_readlane_b32 s18, v252, 3
	v_readlane_b32 s19, v252, 4
	v_readlane_b32 s24, v252, 9
	v_readlane_b32 s25, v252, 10
	v_readlane_b32 s26, v252, 11
	v_readlane_b32 s27, v252, 12
	v_readlane_b32 s28, v252, 13
	v_readlane_b32 s29, v252, 14
	v_readlane_b32 s30, v252, 15
	v_readlane_b32 s31, v252, 16
	s_cbranch_vccnz .LBB0_968
	v_lshlrev_b32_e32 v57, 2, v57
	global_load_dword v57, v57, s[6:7]
	v_add_u32_e32 v59, v5, v10
	global_load_dword v58, v7, s[6:7] offset:8
	s_waitcnt vmcnt(1)
	v_mul_f32_e32 v57, v53, v57
	ds_write_b32 v59, v57
	s_waitcnt vmcnt(0)
	v_mul_f32_e32 v57, v54, v58
	v_add_u32_e32 v58, v5, v17
	ds_write_b32 v58, v57
	global_load_dword v57, v7, s[6:7] offset:16
	global_load_dword v58, v7, s[6:7] offset:24
	s_waitcnt vmcnt(1)
	v_mul_f32_e32 v57, v55, v57
	s_cbranch_execnz .LBB0_904

.LBB0_927:
	s_andn2_b64 vcc, exec, s[0:1]
	s_cbranch_vccnz .LBB0_929
	v_readlane_b32 s16, v252, 1
	s_lshl_b64 s[0:1], s[2:3], 22
	v_readlane_b32 s18, v252, 3
	v_readlane_b32 s19, v252, 4
	s_add_u32 s6, s18, s0
	s_addc_u32 s7, s19, s1
	s_lshl_b64 s[4:5], s[2:3], 21
	v_readlane_b32 s0, v248, 42
	s_add_u32 s1, s0, s4
	v_readlane_b32 s0, v248, 43
	s_addc_u32 s3, s0, s5
	s_lshl_b32 s0, s10, 1
	s_add_i32 s0, s0, 0x1f500
	s_and_b32 s4, s0, 0x1ffc0
	s_lshl_b32 s0, s10, 5
	s_and_b32 s0, s0, 0x3e0
	s_lshl_b32 s5, s0, 2
	s_add_u32 s6, s6, s5
	v_or_b32_e32 v8, s4, v0
	s_addc_u32 s7, s7, 0
	v_lshlrev_b32_e32 v6, 2, v2
	v_mov_b32_e32 v7, v16
	v_lshl_add_u64 v[6:7], s[6:7], 0, v[6:7]
	v_lshlrev_b32_e32 v8, 12, v8
	v_mov_b32_e32 v9, v16
	v_lshl_add_u64 v[6:7], v[6:7], 0, v[8:9]
	s_movk_i32 s5, 0x2000
	v_add_co_u32_e32 v8, vcc, s5, v6
	s_movk_i32 s5, 0x4000
	s_nop 0
	v_addc_co_u32_e32 v9, vcc, 0, v7, vcc
	global_load_dword v28, v[6:7], off nt
	global_load_dword v29, v[8:9], off nt
	v_add_co_u32_e32 v8, vcc, s5, v6
	s_movk_i32 s5, 0x6000
	s_nop 0
	v_addc_co_u32_e32 v9, vcc, 0, v7, vcc
	global_load_dword v30, v[8:9], off nt
	v_add_co_u32_e32 v8, vcc, s5, v6
	s_mov_b32 s5, 0x8000
	s_nop 0
	v_addc_co_u32_e32 v9, vcc, 0, v7, vcc
	global_load_dword v31, v[8:9], off nt
	v_add_co_u32_e32 v8, vcc, s5, v6
	s_mov_b32 s5, 0xa000
	s_nop 0
	v_addc_co_u32_e32 v9, vcc, 0, v7, vcc
	global_load_dword v32, v[8:9], off nt
	v_add_co_u32_e32 v8, vcc, s5, v6
	s_mov_b32 s5, 0xc000
	s_nop 0
	v_addc_co_u32_e32 v9, vcc, 0, v7, vcc
	global_load_dword v33, v[8:9], off nt
	v_add_co_u32_e32 v8, vcc, s5, v6
	s_mov_b32 s5, 0xe000
	s_nop 0
	v_addc_co_u32_e32 v9, vcc, 0, v7, vcc
	global_load_dword v34, v[8:9], off nt
	v_add_co_u32_e32 v8, vcc, s5, v6
	s_mov_b32 s5, 0x10000
	s_nop 0
	v_addc_co_u32_e32 v9, vcc, 0, v7, vcc
	global_load_dword v35, v[8:9], off nt
	v_add_co_u32_e32 v8, vcc, s5, v6
	s_mov_b32 s5, 0x12000
	s_nop 0
	v_addc_co_u32_e32 v9, vcc, 0, v7, vcc
	global_load_dword v36, v[8:9], off nt
	v_add_co_u32_e32 v8, vcc, s5, v6
	s_mov_b32 s5, 0x14000
	s_nop 0
	v_addc_co_u32_e32 v9, vcc, 0, v7, vcc
	global_load_dword v37, v[8:9], off nt
	v_add_co_u32_e32 v8, vcc, s5, v6
	s_mov_b32 s5, 0x16000
	s_nop 0
	v_addc_co_u32_e32 v9, vcc, 0, v7, vcc
	global_load_dword v38, v[8:9], off nt
	v_add_co_u32_e32 v8, vcc, s5, v6
	s_mov_b32 s5, 0x18000
	s_nop 0
	v_addc_co_u32_e32 v9, vcc, 0, v7, vcc
	global_load_dword v39, v[8:9], off nt
	v_add_co_u32_e32 v8, vcc, s5, v6
	s_mov_b32 s5, 0x1a000
	s_nop 0
	v_addc_co_u32_e32 v9, vcc, 0, v7, vcc
	global_load_dword v40, v[8:9], off nt
	v_add_co_u32_e32 v8, vcc, s5, v6
	s_mov_b32 s5, 0x1c000
	s_nop 0
	v_addc_co_u32_e32 v9, vcc, 0, v7, vcc
	global_load_dword v41, v[8:9], off nt
	v_add_co_u32_e32 v8, vcc, s5, v6
	s_mov_b32 s5, 0x1e000
	s_nop 0
	v_addc_co_u32_e32 v9, vcc, 0, v7, vcc
	global_load_dword v42, v[8:9], off nt
	v_add_co_u32_e32 v8, vcc, s5, v6
	s_mov_b32 s5, 0x20000
	s_nop 0
	v_addc_co_u32_e32 v9, vcc, 0, v7, vcc
	global_load_dword v43, v[8:9], off nt
	v_add_co_u32_e32 v8, vcc, s5, v6
	s_mov_b32 s5, 0x22000
	s_nop 0
	v_addc_co_u32_e32 v9, vcc, 0, v7, vcc
	global_load_dword v44, v[8:9], off nt
	v_add_co_u32_e32 v8, vcc, s5, v6
	s_mov_b32 s5, 0x24000
	s_nop 0
	v_addc_co_u32_e32 v9, vcc, 0, v7, vcc
	global_load_dword v45, v[8:9], off nt
	v_add_co_u32_e32 v8, vcc, s5, v6
	s_mov_b32 s5, 0x26000
	s_nop 0
	v_addc_co_u32_e32 v9, vcc, 0, v7, vcc
	global_load_dword v46, v[8:9], off nt
	v_add_co_u32_e32 v8, vcc, s5, v6
	s_mov_b32 s5, 0x28000
	s_nop 0
	v_addc_co_u32_e32 v9, vcc, 0, v7, vcc
	global_load_dword v47, v[8:9], off nt
	v_add_co_u32_e32 v8, vcc, s5, v6
	s_mov_b32 s5, 0x2a000
	s_nop 0
	v_addc_co_u32_e32 v9, vcc, 0, v7, vcc
	global_load_dword v48, v[8:9], off nt
	v_add_co_u32_e32 v8, vcc, s5, v6
	s_mov_b32 s5, 0x2e000
	s_nop 0
	v_addc_co_u32_e32 v9, vcc, 0, v7, vcc
	global_load_dword v49, v[8:9], off nt
	v_add_co_u32_e32 v8, vcc, s44, v6
	s_lshl_b32 s4, s4, 1
	s_nop 0
	v_addc_co_u32_e32 v9, vcc, 0, v7, vcc
	global_load_dword v50, v[8:9], off nt
	v_add_co_u32_e32 v8, vcc, s5, v6
	s_mov_b32 s5, 0x30000
	s_nop 0
	v_addc_co_u32_e32 v9, vcc, 0, v7, vcc
	global_load_dword v51, v[8:9], off nt
	v_add_co_u32_e32 v8, vcc, s5, v6
	s_mov_b32 s5, 0x32000
	s_nop 0
	v_addc_co_u32_e32 v9, vcc, 0, v7, vcc
	global_load_dword v52, v[8:9], off nt
	v_add_co_u32_e32 v8, vcc, s5, v6
	s_mov_b32 s5, 0x34000
	s_nop 0
	v_addc_co_u32_e32 v9, vcc, 0, v7, vcc
	global_load_dword v53, v[8:9], off nt
	v_add_co_u32_e32 v8, vcc, s5, v6
	s_mov_b32 s5, 0x36000
	s_nop 0
	v_addc_co_u32_e32 v9, vcc, 0, v7, vcc
	global_load_dword v54, v[8:9], off nt
	v_add_co_u32_e32 v8, vcc, s5, v6
	s_mov_b32 s5, 0x38000
	s_nop 0
	v_addc_co_u32_e32 v9, vcc, 0, v7, vcc
	global_load_dword v55, v[8:9], off nt
	v_add_co_u32_e32 v8, vcc, s5, v6
	s_mov_b32 s5, 0x3a000
	s_nop 0
	v_addc_co_u32_e32 v9, vcc, 0, v7, vcc
	global_load_dword v56, v[8:9], off nt
	v_add_co_u32_e32 v8, vcc, s5, v6
	s_mov_b32 s5, 0x3c000
	s_nop 0
	v_addc_co_u32_e32 v9, vcc, 0, v7, vcc
	global_load_dword v57, v[8:9], off nt
	v_add_co_u32_e32 v8, vcc, s5, v6
	s_mov_b32 s5, 0x3e000
	s_nop 0
	v_addc_co_u32_e32 v9, vcc, 0, v7, vcc
	v_add_co_u32_e32 v6, vcc, s5, v6
	global_load_dword v8, v[8:9], off nt
	s_nop 0
	v_addc_co_u32_e32 v7, vcc, 0, v7, vcc
	global_load_dword v6, v[6:7], off nt
	v_add_u32_e32 v7, v5, v10
	v_add_u32_e32 v9, 0x400, v7
	s_waitcnt vmcnt(30)
	ds_write2_b32 v7, v28, v29 offset1:66
	s_waitcnt vmcnt(28)
	ds_write2_b32 v7, v30, v31 offset0:132 offset1:198
	s_waitcnt vmcnt(26)
	ds_write2_b32 v9, v32, v33 offset0:8 offset1:74
	s_waitcnt vmcnt(24)
	ds_write2_b32 v9, v34, v35 offset0:140 offset1:206
	v_add_u32_e32 v9, 0x800, v7
	s_waitcnt vmcnt(22)
	ds_write2_b32 v9, v36, v37 offset0:16 offset1:82
	s_waitcnt vmcnt(20)
	ds_write2_b32 v9, v38, v39 offset0:148 offset1:214
	v_add_u32_e32 v9, 0xc00, v7
	s_waitcnt vmcnt(18)
	ds_write2_b32 v9, v40, v41 offset0:24 offset1:90
	s_waitcnt vmcnt(16)
	ds_write2_b32 v9, v42, v43 offset0:156 offset1:222
	v_add_u32_e32 v9, 0x1000, v7
	s_waitcnt vmcnt(14)
	ds_write2_b32 v9, v44, v45 offset0:32 offset1:98
	s_waitcnt vmcnt(12)
	ds_write2_b32 v9, v46, v47 offset0:164 offset1:230
	v_add_u32_e32 v9, 0x1400, v7
	s_waitcnt vmcnt(10)
	ds_write2_b32 v9, v48, v49 offset0:40 offset1:106
	s_waitcnt vmcnt(8)
	ds_write2_b32 v9, v50, v51 offset0:172 offset1:238
	v_add_u32_e32 v9, 0x1800, v7
	v_add_u32_e32 v7, 0x1c00, v7
	s_waitcnt vmcnt(6)
	ds_write2_b32 v9, v52, v53 offset0:48 offset1:114
	s_waitcnt vmcnt(4)
	ds_write2_b32 v9, v54, v55 offset0:180 offset1:246
	s_waitcnt vmcnt(2)
	ds_write2_b32 v7, v56, v57 offset0:56 offset1:122
	s_waitcnt vmcnt(0)
	ds_write2_b32 v7, v8, v6 offset0:188 offset1:254
	s_waitcnt lgkmcnt(0)
	ds_read2_b32 v[8:9], v12 offset1:33
	s_waitcnt lgkmcnt(0)
	v_cvt_pk_bf16_f32 v28, v8, v9
	ds_read2_b32 v[8:9], v12 offset0:66 offset1:99
	s_waitcnt lgkmcnt(0)
	v_cvt_pk_bf16_f32 v29, v8, v9
	ds_read2_b32 v[8:9], v12 offset0:132 offset1:165
	s_add_u32 s4, s1, s4
	s_waitcnt lgkmcnt(0)
	v_cvt_pk_bf16_f32 v30, v8, v9
	ds_read2_b32 v[8:9], v12 offset0:198 offset1:231
	s_addc_u32 s5, s3, 0
	v_lshlrev_b32_e32 v6, 1, v4
	v_mov_b32_e32 v7, v16
	s_waitcnt lgkmcnt(0)
	v_cvt_pk_bf16_f32 v31, v8, v9
	v_or_b32_e32 v8, s0, v11
	v_lshl_add_u64 v[6:7], s[4:5], 0, v[6:7]
	v_lshlrev_b32_e32 v8, 11, v8
	v_mov_b32_e32 v9, v16
	v_lshl_add_u64 v[8:9], v[6:7], 0, v[8:9]
	global_store_dwordx4 v[8:9], v[28:31], off
	ds_read2_b32 v[8:9], v12 offset0:8 offset1:41
	s_mov_b32 s6, 4
	s_waitcnt lgkmcnt(0)
	v_cvt_pk_bf16_f32 v28, v8, v9
	ds_read2_b32 v[8:9], v12 offset0:74 offset1:107
	s_waitcnt lgkmcnt(0)
	v_cvt_pk_bf16_f32 v29, v8, v9
	ds_read2_b32 v[8:9], v12 offset0:140 offset1:173
	s_waitcnt lgkmcnt(0)
	v_cvt_pk_bf16_f32 v30, v8, v9
	ds_read2_b32 v[8:9], v12 offset0:206 offset1:239
	s_waitcnt lgkmcnt(0)
	v_cvt_pk_bf16_f32 v31, v8, v9
	v_or_b32_e32 v8, s0, v13
	v_lshlrev_b32_e32 v8, 11, v8
	v_mov_b32_e32 v9, v16
	v_lshl_add_u64 v[8:9], v[6:7], 0, v[8:9]
	global_store_dwordx4 v[8:9], v[28:31], off
	ds_read2_b32 v[8:9], v12 offset0:16 offset1:49
	v_readlane_b32 s17, v252, 2
	s_waitcnt lgkmcnt(0)
	v_cvt_pk_bf16_f32 v28, v8, v9
	ds_read2_b32 v[8:9], v12 offset0:82 offset1:115
	s_waitcnt lgkmcnt(0)
	v_cvt_pk_bf16_f32 v29, v8, v9
	ds_read2_b32 v[8:9], v12 offset0:148 offset1:181
	s_waitcnt lgkmcnt(0)
	v_cvt_pk_bf16_f32 v30, v8, v9
	ds_read2_b32 v[8:9], v12 offset0:214 offset1:247
	s_waitcnt lgkmcnt(0)
	v_cvt_pk_bf16_f32 v31, v8, v9
	v_or_b32_e32 v8, s0, v14
	v_lshlrev_b32_e32 v8, 11, v8
	v_mov_b32_e32 v9, v16
	v_lshl_add_u64 v[8:9], v[6:7], 0, v[8:9]
	global_store_dwordx4 v[8:9], v[28:31], off
	ds_read2_b32 v[8:9], v12 offset0:24 offset1:57
	v_readlane_b32 s20, v252, 5
	s_waitcnt lgkmcnt(0)
	v_cvt_pk_bf16_f32 v28, v8, v9
	ds_read2_b32 v[8:9], v12 offset0:90 offset1:123
	s_waitcnt lgkmcnt(0)
	v_cvt_pk_bf16_f32 v29, v8, v9
	ds_read2_b32 v[8:9], v12 offset0:156 offset1:189
	s_waitcnt lgkmcnt(0)
	v_cvt_pk_bf16_f32 v30, v8, v9
	ds_read2_b32 v[8:9], v12 offset0:222 offset1:255
	s_waitcnt lgkmcnt(0)
	v_cvt_pk_bf16_f32 v31, v8, v9
	v_or_b32_e32 v8, s0, v15
	v_lshlrev_b32_e32 v8, 11, v8
	v_mov_b32_e32 v9, v16
	v_lshl_add_u64 v[6:7], v[6:7], 0, v[8:9]
	global_store_dwordx4 v[6:7], v[28:31], off
	s_waitcnt lgkmcnt(0)
	v_readlane_b32 s21, v252, 6
	v_readlane_b32 s22, v252, 7
	v_readlane_b32 s23, v252, 8
	v_readlane_b32 s24, v252, 9
	v_readlane_b32 s25, v252, 10
	v_readlane_b32 s26, v252, 11
	v_readlane_b32 s27, v252, 12
	v_readlane_b32 s28, v252, 13
	v_readlane_b32 s29, v252, 14
	v_readlane_b32 s30, v252, 15
	v_readlane_b32 s31, v252, 16

.LBB0_930:
	s_andn2_b64 vcc, exec, s[0:1]
	s_cbranch_vccnz .LBB0_956
	s_mul_i32 s1, s2, 0xb00000
	v_readlane_b32 s4, v252, 36
	s_mul_hi_i32 s0, s2, 0xb00000
	v_readlane_b32 s5, v252, 37
	v_readlane_b32 s7, v252, 39
	s_add_u32 s3, s4, s1
	s_addc_u32 s7, s5, s0
	s_lshl_b32 s0, s2, 10
	s_ashr_i32 s1, s0, 31
	v_readlane_b32 s16, v251, 52
	s_lshl_b64 s[0:1], s[0:1], 2
	v_readlane_b32 s22, v251, 58
	v_readlane_b32 s23, v251, 59
	s_add_u32 s8, s22, s0
	s_mul_i32 s0, s10, 0xba3
	s_addc_u32 s9, s23, s1
	s_lshr_b32 s1, s0, 31
	s_ashr_i32 s0, s0, 18
	s_add_i32 s0, s0, s1
	s_mul_i32 s1, s0, 0x58
	s_sub_i32 s1, s10, s1
	s_sext_i32_i16 s1, s1
	s_lshl_b32 s4, s1, 5
	v_readlane_b32 s6, v252, 38
	s_ashr_i32 s5, s4, 31
	s_lshl_b32 s6, s0, 6
	s_lshl_b64 s[0:1], s[4:5], 2
	s_add_u32 s0, s3, s0
	v_or_b32_e32 v6, s6, v0
	s_addc_u32 s1, s7, s1
	v_lshlrev_b32_e32 v8, 2, v2
	v_mov_b32_e32 v9, v16
	v_lshl_add_u64 v[8:9], s[0:1], 0, v[8:9]
	v_mul_hi_i32_i24_e32 v29, 0x2c00, v6
	v_mul_i32_i24_e32 v28, 0x2c00, v6
	v_lshl_add_u64 v[28:29], v[8:9], 0, v[28:29]
	global_load_dword v55, v[28:29], off nt
	v_mul_i32_i24_e32 v28, 0xb00, v6
	v_ashrrev_i32_e32 v29, 31, v28
	v_lshl_add_u64 v[8:9], v[28:29], 2, v[8:9]
	s_movk_i32 s0, 0x5000
	v_add_co_u32_e32 v28, vcc, s0, v8
	s_mov_b32 s0, 0xb000
	s_nop 0
	v_addc_co_u32_e32 v29, vcc, 0, v9, vcc
	global_load_dword v56, v[28:29], off offset:2048 nt
	v_add_co_u32_e32 v28, vcc, s0, v8
	s_mov_b32 s0, 0x10000
	s_nop 0
	v_addc_co_u32_e32 v29, vcc, 0, v9, vcc
	global_load_dword v57, v[28:29], off nt
	v_add_co_u32_e32 v28, vcc, s0, v8
	s_mov_b32 s0, 0x16000
	s_nop 0
	v_addc_co_u32_e32 v29, vcc, 0, v9, vcc
	global_load_dword v58, v[28:29], off offset:2048 nt
	v_add_co_u32_e32 v28, vcc, s0, v8
	s_mov_b32 s0, 0x1b000
	s_nop 0
	v_addc_co_u32_e32 v29, vcc, 0, v9, vcc
	global_load_dword v51, v[28:29], off nt
	v_add_co_u32_e32 v28, vcc, s0, v8
	s_mov_b32 s0, 0x21000
	s_nop 0
	v_addc_co_u32_e32 v29, vcc, 0, v9, vcc
	global_load_dword v52, v[28:29], off offset:2048 nt
	v_add_co_u32_e32 v28, vcc, s0, v8
	s_mov_b32 s0, 0x26000
	s_nop 0
	v_addc_co_u32_e32 v29, vcc, 0, v9, vcc
	global_load_dword v53, v[28:29], off nt
	v_add_co_u32_e32 v28, vcc, s0, v8
	s_mov_b32 s0, 0x31000
	s_nop 0
	v_addc_co_u32_e32 v29, vcc, 0, v9, vcc
	global_load_dword v54, v[28:29], off offset:2048 nt
	v_add_co_u32_e32 v28, vcc, s44, v8
	v_cndmask_b32_e64 v7, 0, 1, s[50:51]
	s_nop 0
	v_addc_co_u32_e32 v29, vcc, 0, v9, vcc
	global_load_dword v47, v[28:29], off nt
	v_add_co_u32_e32 v28, vcc, s0, v8
	s_mov_b32 s0, 0x37000
	s_nop 0
	v_addc_co_u32_e32 v29, vcc, 0, v9, vcc
	global_load_dword v48, v[28:29], off offset:2048 nt
	v_add_co_u32_e32 v28, vcc, s0, v8
	s_mov_b32 s0, 0x3c000
	s_nop 0
	v_addc_co_u32_e32 v29, vcc, 0, v9, vcc
	global_load_dword v49, v[28:29], off nt
	v_add_co_u32_e32 v28, vcc, s0, v8
	s_mov_b32 s0, 0x42000
	s_nop 0
	v_addc_co_u32_e32 v29, vcc, 0, v9, vcc
	global_load_dword v50, v[28:29], off offset:2048 nt
	v_add_co_u32_e32 v28, vcc, s0, v8
	s_mov_b32 s0, 0x47000
	s_nop 0
	v_addc_co_u32_e32 v29, vcc, 0, v9, vcc
	global_load_dword v43, v[28:29], off nt
	v_add_co_u32_e32 v28, vcc, s0, v8
	s_mov_b32 s0, 0x4d000
	s_nop 0
	v_addc_co_u32_e32 v29, vcc, 0, v9, vcc
	global_load_dword v44, v[28:29], off offset:2048 nt
	v_add_co_u32_e32 v28, vcc, s0, v8
	s_mov_b32 s0, 0x52000
	s_nop 0
	v_addc_co_u32_e32 v29, vcc, 0, v9, vcc
	global_load_dword v45, v[28:29], off nt
	v_add_co_u32_e32 v28, vcc, s0, v8
	s_mov_b32 s0, 0x58000
	s_nop 0
	v_addc_co_u32_e32 v29, vcc, 0, v9, vcc
	global_load_dword v46, v[28:29], off offset:2048 nt
	v_add_co_u32_e32 v28, vcc, s0, v8
	s_mov_b32 s0, 0x5d000
	s_nop 0
	v_addc_co_u32_e32 v29, vcc, 0, v9, vcc
	global_load_dword v39, v[28:29], off nt
	v_add_co_u32_e32 v28, vcc, s0, v8
	s_mov_b32 s0, 0x63000
	s_nop 0
	v_addc_co_u32_e32 v29, vcc, 0, v9, vcc
	global_load_dword v40, v[28:29], off offset:2048 nt
	v_add_co_u32_e32 v28, vcc, s0, v8
	s_mov_b32 s0, 0x68000
	s_nop 0
	v_addc_co_u32_e32 v29, vcc, 0, v9, vcc
	global_load_dword v41, v[28:29], off nt
	v_add_co_u32_e32 v28, vcc, s0, v8
	s_mov_b32 s0, 0x6e000
	s_nop 0
	v_addc_co_u32_e32 v29, vcc, 0, v9, vcc
	global_load_dword v42, v[28:29], off offset:2048 nt
	v_add_co_u32_e32 v28, vcc, s0, v8
	s_mov_b32 s0, 0x73000
	s_nop 0
	v_addc_co_u32_e32 v29, vcc, 0, v9, vcc
	global_load_dword v35, v[28:29], off nt
	v_add_co_u32_e32 v28, vcc, s0, v8
	s_mov_b32 s0, 0x79000
	s_nop 0
	v_addc_co_u32_e32 v29, vcc, 0, v9, vcc
	global_load_dword v36, v[28:29], off offset:2048 nt
	v_add_co_u32_e32 v28, vcc, s0, v8
	s_mov_b32 s0, 0x7e000
	s_nop 0
	v_addc_co_u32_e32 v29, vcc, 0, v9, vcc
	global_load_dword v37, v[28:29], off nt
	v_add_co_u32_e32 v28, vcc, s0, v8
	s_mov_b32 s0, 0x84000
	s_nop 0
	v_addc_co_u32_e32 v29, vcc, 0, v9, vcc
	global_load_dword v38, v[28:29], off offset:2048 nt
	v_add_co_u32_e32 v28, vcc, s0, v8
	s_mov_b32 s0, 0x89000
	s_nop 0
	v_addc_co_u32_e32 v29, vcc, 0, v9, vcc
	global_load_dword v31, v[28:29], off nt
	v_add_co_u32_e32 v28, vcc, s0, v8
	s_mov_b32 s0, 0x8f000
	s_nop 0
	v_addc_co_u32_e32 v29, vcc, 0, v9, vcc
	global_load_dword v32, v[28:29], off offset:2048 nt
	v_add_co_u32_e32 v28, vcc, s0, v8
	s_mov_b32 s0, 0x94000
	s_nop 0
	v_addc_co_u32_e32 v29, vcc, 0, v9, vcc
	global_load_dword v33, v[28:29], off nt
	v_add_co_u32_e32 v28, vcc, s0, v8
	s_mov_b32 s0, 0x9a000
	s_nop 0
	v_addc_co_u32_e32 v29, vcc, 0, v9, vcc
	global_load_dword v34, v[28:29], off offset:2048 nt
	v_add_co_u32_e32 v28, vcc, s0, v8
	v_cmp_ne_u32_e64 s[0:1], 1, v7
	s_nop 0
	v_addc_co_u32_e32 v29, vcc, 0, v9, vcc
	v_add_co_u32_e32 v60, vcc, 0x9f000, v8
	global_load_dword v28, v[28:29], off nt
	s_nop 0
	v_addc_co_u32_e32 v61, vcc, 0, v9, vcc
	global_load_dword v29, v[60:61], off offset:2048 nt
	v_add_co_u32_e32 v60, vcc, 0xa5000, v8
	v_add_u32_e32 v59, v5, v17
	s_nop 0
	v_addc_co_u32_e32 v61, vcc, 0, v9, vcc
	v_add_co_u32_e32 v8, vcc, 0xaa000, v8
	global_load_dword v30, v[60:61], off nt
	s_nop 0
	v_addc_co_u32_e32 v9, vcc, 0, v9, vcc
	global_load_dword v8, v[8:9], off offset:2048 nt
	s_andn2_b64 vcc, exec, s[50:51]
	v_add_u32_e32 v9, v5, v10
	v_readlane_b32 s17, v251, 53
	v_readlane_b32 s18, v251, 54
	v_readlane_b32 s19, v251, 55
	v_readlane_b32 s20, v251, 56
	v_readlane_b32 s21, v251, 57
	s_cbranch_vccnz .LBB0_960
	v_ashrrev_i32_e32 v7, 31, v6
	v_lshl_add_u64 v[6:7], v[6:7], 2, s[8:9]
	global_load_dword v6, v[6:7], off nt
	s_ashr_i32 s7, s6, 31
	s_waitcnt vmcnt(0)
	v_mul_f32_e32 v62, v55, v6
	v_lshl_add_u64 v[6:7], s[6:7], 0, v[0:1]
	v_lshl_add_u64 v[60:61], v[6:7], 2, s[8:9]
	global_load_dword v6, v[60:61], off offset:8 nt
	global_load_dword v7, v[60:61], off offset:24 nt
	ds_write_b32 v9, v62
	s_waitcnt vmcnt(1)
	v_mul_f32_e32 v6, v56, v6
	ds_write_b32 v59, v6
	global_load_dword v6, v[60:61], off offset:16 nt
	s_waitcnt vmcnt(0)
	v_mul_f32_e32 v6, v57, v6
	s_cbranch_execnz .LBB0_934

.LBB0_934:
	v_add_u32_e32 v9, v5, v18
	s_waitcnt vmcnt(28)
	v_mul_f32_e32 v7, v58, v7
	ds_write2_b32 v9, v6, v7 offset1:66
	s_and_b64 vcc, exec, s[0:1]
	v_add_u32_e32 v6, v5, v19
	s_cbranch_vccnz .LBB0_961
	s_ashr_i32 s7, s6, 31
	v_lshl_add_u64 v[56:57], s[6:7], 0, v[0:1]
	v_lshl_add_u64 v[56:57], v[56:57], 2, s[8:9]
	global_load_dword v7, v[56:57], off offset:32 nt
	global_load_dword v9, v[56:57], off offset:40 nt
	s_waitcnt vmcnt(1)
	v_mul_f32_e32 v7, v51, v7
	s_waitcnt vmcnt(0)
	v_mul_f32_e32 v9, v52, v9
	ds_write2_b32 v6, v7, v9 offset1:66
	global_load_dword v7, v[56:57], off offset:48 nt
	global_load_dword v9, v[56:57], off offset:56 nt
	s_waitcnt vmcnt(1)
	v_mul_f32_e32 v7, v53, v7
	s_cbranch_execnz .LBB0_937

.LBB0_937:
	v_add_u32_e32 v6, v5, v20
	s_waitcnt vmcnt(0)
	v_mul_f32_e32 v9, v54, v9
	ds_write2_b32 v6, v7, v9 offset1:66
	s_and_b64 vcc, exec, s[0:1]
	v_add_u32_e32 v6, v5, v21
	s_cbranch_vccnz .LBB0_962
	s_ashr_i32 s7, s6, 31
	v_lshl_add_u64 v[52:53], s[6:7], 0, v[0:1]
	v_lshl_add_u64 v[52:53], v[52:53], 2, s[8:9]
	global_load_dword v7, v[52:53], off offset:64 nt
	global_load_dword v9, v[52:53], off offset:72 nt
	s_waitcnt vmcnt(1)
	v_mul_f32_e32 v7, v47, v7
	s_waitcnt vmcnt(0)
	v_mul_f32_e32 v9, v48, v9
	ds_write2_b32 v6, v7, v9 offset1:66
	global_load_dword v7, v[52:53], off offset:80 nt
	global_load_dword v9, v[52:53], off offset:88 nt
	s_waitcnt vmcnt(1)
	v_mul_f32_e32 v7, v49, v7
	s_cbranch_execnz .LBB0_940

.LBB0_940:
	v_add_u32_e32 v6, v5, v22
	s_waitcnt vmcnt(0)
	v_mul_f32_e32 v9, v50, v9
	ds_write2_b32 v6, v7, v9 offset1:66
	s_and_b64 vcc, exec, s[0:1]
	v_add_u32_e32 v6, v5, v23
	s_cbranch_vccnz .LBB0_963
	s_ashr_i32 s7, s6, 31
	v_lshl_add_u64 v[48:49], s[6:7], 0, v[0:1]
	v_lshl_add_u64 v[48:49], v[48:49], 2, s[8:9]
	global_load_dword v7, v[48:49], off offset:96 nt
	global_load_dword v9, v[48:49], off offset:104 nt
	s_waitcnt vmcnt(1)
	v_mul_f32_e32 v7, v43, v7
	s_waitcnt vmcnt(0)
	v_mul_f32_e32 v9, v44, v9
	ds_write2_b32 v6, v7, v9 offset1:66
	global_load_dword v7, v[48:49], off offset:112 nt
	global_load_dword v9, v[48:49], off offset:120 nt
	s_waitcnt vmcnt(1)
	v_mul_f32_e32 v7, v45, v7
	s_cbranch_execnz .LBB0_943

.LBB0_943:
	v_add_u32_e32 v6, v5, v24
	s_waitcnt vmcnt(0)
	v_mul_f32_e32 v9, v46, v9
	ds_write2_b32 v6, v7, v9 offset1:66
	s_and_b64 vcc, exec, s[0:1]
	v_add_u32_e32 v6, v5, v25
	s_cbranch_vccnz .LBB0_964
	s_ashr_i32 s7, s6, 31
	v_lshl_add_u64 v[44:45], s[6:7], 0, v[0:1]
	v_lshl_add_u64 v[44:45], v[44:45], 2, s[8:9]
	global_load_dword v7, v[44:45], off offset:128 nt
	global_load_dword v9, v[44:45], off offset:136 nt
	s_waitcnt vmcnt(1)
	v_mul_f32_e32 v7, v39, v7
	s_waitcnt vmcnt(0)
	v_mul_f32_e32 v9, v40, v9
	ds_write2_b32 v6, v7, v9 offset1:66
	global_load_dword v7, v[44:45], off offset:144 nt
	global_load_dword v9, v[44:45], off offset:152 nt
	s_waitcnt vmcnt(1)
	v_mul_f32_e32 v7, v41, v7
	s_cbranch_execnz .LBB0_946

.LBB0_946:
	v_add_u32_e32 v6, v5, v26
	s_waitcnt vmcnt(0)
	v_mul_f32_e32 v9, v42, v9
	ds_write2_b32 v6, v7, v9 offset1:66
	s_and_b64 vcc, exec, s[0:1]
	v_add_u32_e32 v6, v5, v27
	s_cbranch_vccnz .LBB0_965
	s_ashr_i32 s7, s6, 31
	v_lshl_add_u64 v[40:41], s[6:7], 0, v[0:1]
	v_lshl_add_u64 v[40:41], v[40:41], 2, s[8:9]
	global_load_dword v7, v[40:41], off offset:160 nt
	global_load_dword v9, v[40:41], off offset:168 nt
	s_waitcnt vmcnt(1)
	v_mul_f32_e32 v7, v35, v7
	s_waitcnt vmcnt(0)
	v_mul_f32_e32 v9, v36, v9
	ds_write2_b32 v6, v7, v9 offset1:66
	global_load_dword v7, v[40:41], off offset:176 nt
	global_load_dword v9, v[40:41], off offset:184 nt
	s_waitcnt vmcnt(1)
	v_mul_f32_e32 v7, v37, v7
	s_cbranch_execnz .LBB0_949

.LBB0_949:
	s_waitcnt vmcnt(0)
	v_mul_f32_e32 v9, v38, v9
	ds_write2_b32 v6, v7, v9 offset0:132 offset1:198
	s_and_b64 vcc, exec, s[0:1]
	v_add_u32_e32 v7, 0x400, v6
	s_cbranch_vccnz .LBB0_966
	s_ashr_i32 s7, s6, 31
	v_lshl_add_u64 v[36:37], s[6:7], 0, v[0:1]
	v_lshl_add_u64 v[36:37], v[36:37], 2, s[8:9]
	global_load_dword v9, v[36:37], off offset:192 nt
	global_load_dword v35, v[36:37], off offset:200 nt
	s_waitcnt vmcnt(1)
	v_mul_f32_e32 v9, v31, v9
	s_waitcnt vmcnt(0)
	v_mul_f32_e32 v35, v32, v35
	ds_write2_b32 v7, v9, v35 offset0:8 offset1:74
	global_load_dword v9, v[36:37], off offset:208 nt
	global_load_dword v35, v[36:37], off offset:216 nt
	s_waitcnt vmcnt(1)
	v_mul_f32_e32 v9, v33, v9
	s_cbranch_execnz .LBB0_952

.LBB0_952:
	s_waitcnt vmcnt(0)
	v_mul_f32_e32 v31, v34, v35
	s_and_b64 vcc, exec, s[0:1]
	v_add_u32_e32 v6, 0x800, v6
	ds_write2_b32 v7, v9, v31 offset0:140 offset1:206
	s_cbranch_vccnz .LBB0_967
	s_ashr_i32 s7, s6, 31
	v_lshl_add_u64 v[32:33], s[6:7], 0, v[0:1]
	v_lshl_add_u64 v[32:33], v[32:33], 2, s[8:9]
	global_load_dword v7, v[32:33], off offset:224 nt
	global_load_dword v9, v[32:33], off offset:232 nt
	s_waitcnt vmcnt(1)
	v_mul_f32_e32 v7, v28, v7
	s_waitcnt vmcnt(0)
	v_mul_f32_e32 v9, v29, v9
	ds_write2_b32 v6, v7, v9 offset0:16 offset1:82
	global_load_dword v7, v[32:33], off offset:240 nt
	global_load_dword v9, v[32:33], off offset:248 nt
	s_waitcnt vmcnt(1)
	v_mul_f32_e32 v7, v30, v7
	s_cbranch_execnz .LBB0_955

.LBB0_1382:
	s_mul_i32 s0, s12, 0x1780
	s_cmp_ge_i32 s13, s0
	s_mov_b32 s6, 2
	s_cbranch_scc1 .LBB0_1443
	s_mul_hi_i32 s0, s13, 0xae4c415d
	s_add_i32 s0, s0, s13
	s_lshr_b32 s1, s0, 31
	s_ashr_i32 s0, s0, 12
	s_add_i32 s2, s0, s1
	s_mul_i32 s0, s2, 0x1780
	s_sub_i32 s10, s13, s0
	s_ashr_i32 s3, s2, 31
	s_cmpk_gt_i32 s10, 0x57f
	s_mov_b64 s[0:1], -1
	s_cbranch_scc0 .LBB0_1417
	s_cmpk_gt_u32 s10, 0x77f
	s_cbranch_scc0 .LBB0_1414
	s_lshl_b64 s[0:1], s[2:3], 24
	s_lshl_b64 s[4:5], s[2:3], 23
	s_cmpk_gt_u32 s10, 0xf7f
	s_mov_b64 s[6:7], -1
	s_cbranch_scc0 .LBB0_1387
	v_readlane_b32 s16, v252, 1
	v_readlane_b32 s24, v252, 9
	v_readlane_b32 s25, v252, 10
	s_add_u32 s11, s24, s0
	s_addc_u32 s15, s25, s1
	v_readlane_b32 s6, v248, 38
	s_add_u32 s7, s6, s4
	v_readlane_b32 s6, v248, 39
	s_addc_u32 s8, s6, s5
	s_lshl_b32 s6, s10, 1
	s_add_i32 s6, s6, 0x1e100
	s_and_b32 s9, s6, 0x1ffc0
	s_lshl_b32 s6, s10, 5
	s_and_b32 s6, s6, 0x3e0
	s_lshl_b32 s16, s6, 2
	v_readlane_b32 s17, v252, 2
	s_add_u32 s16, s11, s16
	v_or_b32_e32 v8, s9, v0
	s_addc_u32 s17, s15, 0
	v_lshlrev_b32_e32 v6, 2, v2
	v_mov_b32_e32 v7, v16
	v_lshl_add_u64 v[6:7], s[16:17], 0, v[6:7]
	v_lshlrev_b32_e32 v8, 12, v8
	v_mov_b32_e32 v9, v16
	v_lshl_add_u64 v[6:7], v[6:7], 0, v[8:9]
	s_movk_i32 s11, 0x2000
	v_add_co_u32_e32 v8, vcc, s11, v6
	s_movk_i32 s11, 0x4000
	s_nop 0
	v_addc_co_u32_e32 v9, vcc, 0, v7, vcc
	global_load_dword v28, v[6:7], off nt
	global_load_dword v29, v[8:9], off nt
	v_add_co_u32_e32 v8, vcc, s11, v6
	s_movk_i32 s11, 0x6000
	s_nop 0
	v_addc_co_u32_e32 v9, vcc, 0, v7, vcc
	global_load_dword v30, v[8:9], off nt
	v_add_co_u32_e32 v8, vcc, s11, v6
	s_mov_b32 s11, 0x8000
	s_nop 0
	v_addc_co_u32_e32 v9, vcc, 0, v7, vcc
	global_load_dword v31, v[8:9], off nt
	v_add_co_u32_e32 v8, vcc, s11, v6
	s_mov_b32 s11, 0xa000
	s_nop 0
	v_addc_co_u32_e32 v9, vcc, 0, v7, vcc
	global_load_dword v32, v[8:9], off nt
	v_add_co_u32_e32 v8, vcc, s11, v6
	s_mov_b32 s11, 0xc000
	s_nop 0
	v_addc_co_u32_e32 v9, vcc, 0, v7, vcc
	global_load_dword v33, v[8:9], off nt
	v_add_co_u32_e32 v8, vcc, s11, v6
	s_mov_b32 s11, 0xe000
	s_nop 0
	v_addc_co_u32_e32 v9, vcc, 0, v7, vcc
	global_load_dword v34, v[8:9], off nt
	v_add_co_u32_e32 v8, vcc, s11, v6
	s_mov_b32 s11, 0x10000
	s_nop 0
	v_addc_co_u32_e32 v9, vcc, 0, v7, vcc
	global_load_dword v35, v[8:9], off nt
	v_add_co_u32_e32 v8, vcc, s11, v6
	s_mov_b32 s11, 0x12000
	s_nop 0
	v_addc_co_u32_e32 v9, vcc, 0, v7, vcc
	global_load_dword v36, v[8:9], off nt
	v_add_co_u32_e32 v8, vcc, s11, v6
	s_mov_b32 s11, 0x14000
	s_nop 0
	v_addc_co_u32_e32 v9, vcc, 0, v7, vcc
	global_load_dword v37, v[8:9], off nt
	v_add_co_u32_e32 v8, vcc, s11, v6
	s_mov_b32 s11, 0x16000
	s_nop 0
	v_addc_co_u32_e32 v9, vcc, 0, v7, vcc
	global_load_dword v38, v[8:9], off nt
	v_add_co_u32_e32 v8, vcc, s11, v6
	s_mov_b32 s11, 0x18000
	s_nop 0
	v_addc_co_u32_e32 v9, vcc, 0, v7, vcc
	global_load_dword v39, v[8:9], off nt
	v_add_co_u32_e32 v8, vcc, s11, v6
	s_mov_b32 s11, 0x1a000
	s_nop 0
	v_addc_co_u32_e32 v9, vcc, 0, v7, vcc
	global_load_dword v40, v[8:9], off nt
	v_add_co_u32_e32 v8, vcc, s11, v6
	s_mov_b32 s11, 0x1c000
	s_nop 0
	v_addc_co_u32_e32 v9, vcc, 0, v7, vcc
	global_load_dword v41, v[8:9], off nt
	v_add_co_u32_e32 v8, vcc, s11, v6
	s_mov_b32 s11, 0x1e000
	s_nop 0
	v_addc_co_u32_e32 v9, vcc, 0, v7, vcc
	global_load_dword v42, v[8:9], off nt
	v_add_co_u32_e32 v8, vcc, s11, v6
	s_mov_b32 s11, 0x20000
	s_nop 0
	v_addc_co_u32_e32 v9, vcc, 0, v7, vcc
	global_load_dword v43, v[8:9], off nt
	v_add_co_u32_e32 v8, vcc, s11, v6
	s_mov_b32 s11, 0x22000
	s_nop 0
	v_addc_co_u32_e32 v9, vcc, 0, v7, vcc
	global_load_dword v44, v[8:9], off nt
	v_add_co_u32_e32 v8, vcc, s11, v6
	s_mov_b32 s11, 0x24000
	s_nop 0
	v_addc_co_u32_e32 v9, vcc, 0, v7, vcc
	global_load_dword v45, v[8:9], off nt
	v_add_co_u32_e32 v8, vcc, s11, v6
	s_mov_b32 s11, 0x26000
	s_nop 0
	v_addc_co_u32_e32 v9, vcc, 0, v7, vcc
	global_load_dword v46, v[8:9], off nt
	v_add_co_u32_e32 v8, vcc, s11, v6
	s_mov_b32 s11, 0x28000
	s_nop 0
	v_addc_co_u32_e32 v9, vcc, 0, v7, vcc
	global_load_dword v47, v[8:9], off nt
	v_add_co_u32_e32 v8, vcc, s11, v6
	s_mov_b32 s11, 0x2a000
	s_nop 0
	v_addc_co_u32_e32 v9, vcc, 0, v7, vcc
	global_load_dword v48, v[8:9], off nt
	v_add_co_u32_e32 v8, vcc, s11, v6
	s_mov_b32 s11, 0x2e000
	s_nop 0
	v_addc_co_u32_e32 v9, vcc, 0, v7, vcc
	global_load_dword v49, v[8:9], off nt
	v_add_co_u32_e32 v8, vcc, s44, v6
	s_lshl_b32 s9, s9, 1
	s_nop 0
	v_addc_co_u32_e32 v9, vcc, 0, v7, vcc
	global_load_dword v50, v[8:9], off nt
	v_add_co_u32_e32 v8, vcc, s11, v6
	s_mov_b32 s11, 0x30000
	s_nop 0
	v_addc_co_u32_e32 v9, vcc, 0, v7, vcc
	global_load_dword v51, v[8:9], off nt
	v_add_co_u32_e32 v8, vcc, s11, v6
	s_mov_b32 s11, 0x32000
	s_nop 0
	v_addc_co_u32_e32 v9, vcc, 0, v7, vcc
	global_load_dword v52, v[8:9], off nt
	v_add_co_u32_e32 v8, vcc, s11, v6
	s_mov_b32 s11, 0x34000
	s_nop 0
	v_addc_co_u32_e32 v9, vcc, 0, v7, vcc
	global_load_dword v53, v[8:9], off nt
	v_add_co_u32_e32 v8, vcc, s11, v6
	s_mov_b32 s11, 0x36000
	s_nop 0
	v_addc_co_u32_e32 v9, vcc, 0, v7, vcc
	global_load_dword v54, v[8:9], off nt
	v_add_co_u32_e32 v8, vcc, s11, v6
	s_mov_b32 s11, 0x38000
	s_nop 0
	v_addc_co_u32_e32 v9, vcc, 0, v7, vcc
	global_load_dword v55, v[8:9], off nt
	v_add_co_u32_e32 v8, vcc, s11, v6
	s_mov_b32 s11, 0x3a000
	s_nop 0
	v_addc_co_u32_e32 v9, vcc, 0, v7, vcc
	global_load_dword v56, v[8:9], off nt
	v_add_co_u32_e32 v8, vcc, s11, v6
	s_mov_b32 s11, 0x3c000
	s_nop 0
	v_addc_co_u32_e32 v9, vcc, 0, v7, vcc
	global_load_dword v57, v[8:9], off nt
	v_add_co_u32_e32 v8, vcc, s11, v6
	s_mov_b32 s11, 0x3e000
	s_nop 0
	v_addc_co_u32_e32 v9, vcc, 0, v7, vcc
	v_add_co_u32_e32 v6, vcc, s11, v6
	global_load_dword v8, v[8:9], off nt
	s_nop 0
	v_addc_co_u32_e32 v7, vcc, 0, v7, vcc
	global_load_dword v6, v[6:7], off nt
	v_add_u32_e32 v7, v5, v10
	v_add_u32_e32 v9, 0x400, v7
	s_waitcnt vmcnt(30)
	ds_write2_b32 v7, v28, v29 offset1:66
	s_waitcnt vmcnt(28)
	ds_write2_b32 v7, v30, v31 offset0:132 offset1:198
	s_waitcnt vmcnt(26)
	ds_write2_b32 v9, v32, v33 offset0:8 offset1:74
	s_waitcnt vmcnt(24)
	ds_write2_b32 v9, v34, v35 offset0:140 offset1:206
	v_add_u32_e32 v9, 0x800, v7
	s_waitcnt vmcnt(22)
	ds_write2_b32 v9, v36, v37 offset0:16 offset1:82
	s_waitcnt vmcnt(20)
	ds_write2_b32 v9, v38, v39 offset0:148 offset1:214
	v_add_u32_e32 v9, 0xc00, v7
	s_waitcnt vmcnt(18)
	ds_write2_b32 v9, v40, v41 offset0:24 offset1:90
	s_waitcnt vmcnt(16)
	ds_write2_b32 v9, v42, v43 offset0:156 offset1:222
	v_add_u32_e32 v9, 0x1000, v7
	s_waitcnt vmcnt(14)
	ds_write2_b32 v9, v44, v45 offset0:32 offset1:98
	s_waitcnt vmcnt(12)
	ds_write2_b32 v9, v46, v47 offset0:164 offset1:230
	v_add_u32_e32 v9, 0x1400, v7
	s_waitcnt vmcnt(10)
	ds_write2_b32 v9, v48, v49 offset0:40 offset1:106
	s_waitcnt vmcnt(8)
	ds_write2_b32 v9, v50, v51 offset0:172 offset1:238
	v_add_u32_e32 v9, 0x1800, v7
	v_add_u32_e32 v7, 0x1c00, v7
	s_waitcnt vmcnt(6)
	ds_write2_b32 v9, v52, v53 offset0:48 offset1:114
	s_waitcnt vmcnt(4)
	ds_write2_b32 v9, v54, v55 offset0:180 offset1:246
	s_waitcnt vmcnt(2)
	ds_write2_b32 v7, v56, v57 offset0:56 offset1:122
	s_waitcnt vmcnt(0)
	ds_write2_b32 v7, v8, v6 offset0:188 offset1:254
	s_waitcnt lgkmcnt(0)
	ds_read2_b32 v[8:9], v12 offset1:33
	s_waitcnt lgkmcnt(0)
	v_cvt_pk_bf16_f32 v28, v8, v9
	ds_read2_b32 v[8:9], v12 offset0:66 offset1:99
	s_waitcnt lgkmcnt(0)
	v_cvt_pk_bf16_f32 v29, v8, v9
	ds_read2_b32 v[8:9], v12 offset0:132 offset1:165
	s_add_u32 s16, s7, s9
	s_waitcnt lgkmcnt(0)
	v_cvt_pk_bf16_f32 v30, v8, v9
	ds_read2_b32 v[8:9], v12 offset0:198 offset1:231
	s_addc_u32 s17, s8, 0
	v_lshlrev_b32_e32 v6, 1, v4
	v_mov_b32_e32 v7, v16
	s_waitcnt lgkmcnt(0)
	v_cvt_pk_bf16_f32 v31, v8, v9
	v_or_b32_e32 v8, s6, v11
	v_lshl_add_u64 v[6:7], s[16:17], 0, v[6:7]
	v_lshlrev_b32_e32 v8, 13, v8
	v_mov_b32_e32 v9, v16
	v_lshl_add_u64 v[8:9], v[6:7], 0, v[8:9]
	global_store_dwordx4 v[8:9], v[28:31], off
	ds_read2_b32 v[8:9], v12 offset0:8 offset1:41
	v_readlane_b32 s18, v252, 3
	s_waitcnt lgkmcnt(0)
	v_cvt_pk_bf16_f32 v28, v8, v9
	ds_read2_b32 v[8:9], v12 offset0:74 offset1:107
	s_waitcnt lgkmcnt(0)
	v_cvt_pk_bf16_f32 v29, v8, v9
	ds_read2_b32 v[8:9], v12 offset0:140 offset1:173
	s_waitcnt lgkmcnt(0)
	v_cvt_pk_bf16_f32 v30, v8, v9
	ds_read2_b32 v[8:9], v12 offset0:206 offset1:239
	s_waitcnt lgkmcnt(0)
	v_cvt_pk_bf16_f32 v31, v8, v9
	v_or_b32_e32 v8, s6, v13
	v_lshlrev_b32_e32 v8, 13, v8
	v_mov_b32_e32 v9, v16
	v_lshl_add_u64 v[8:9], v[6:7], 0, v[8:9]
	global_store_dwordx4 v[8:9], v[28:31], off
	ds_read2_b32 v[8:9], v12 offset0:16 offset1:49
	v_readlane_b32 s19, v252, 4
	s_waitcnt lgkmcnt(0)
	v_cvt_pk_bf16_f32 v28, v8, v9
	ds_read2_b32 v[8:9], v12 offset0:82 offset1:115
	s_waitcnt lgkmcnt(0)
	v_cvt_pk_bf16_f32 v29, v8, v9
	ds_read2_b32 v[8:9], v12 offset0:148 offset1:181
	s_waitcnt lgkmcnt(0)
	v_cvt_pk_bf16_f32 v30, v8, v9
	ds_read2_b32 v[8:9], v12 offset0:214 offset1:247
	s_waitcnt lgkmcnt(0)
	v_cvt_pk_bf16_f32 v31, v8, v9
	v_or_b32_e32 v8, s6, v14
	v_lshlrev_b32_e32 v8, 13, v8
	v_mov_b32_e32 v9, v16
	v_lshl_add_u64 v[8:9], v[6:7], 0, v[8:9]
	global_store_dwordx4 v[8:9], v[28:31], off
	ds_read2_b32 v[8:9], v12 offset0:24 offset1:57
	v_readlane_b32 s20, v252, 5
	s_waitcnt lgkmcnt(0)
	v_cvt_pk_bf16_f32 v28, v8, v9
	ds_read2_b32 v[8:9], v12 offset0:90 offset1:123
	s_waitcnt lgkmcnt(0)
	v_cvt_pk_bf16_f32 v29, v8, v9
	ds_read2_b32 v[8:9], v12 offset0:156 offset1:189
	s_waitcnt lgkmcnt(0)
	v_cvt_pk_bf16_f32 v30, v8, v9
	ds_read2_b32 v[8:9], v12 offset0:222 offset1:255
	s_waitcnt lgkmcnt(0)
	v_cvt_pk_bf16_f32 v31, v8, v9
	v_or_b32_e32 v8, s6, v15
	v_lshlrev_b32_e32 v8, 13, v8
	v_mov_b32_e32 v9, v16
	v_lshl_add_u64 v[6:7], v[6:7], 0, v[8:9]
	global_store_dwordx4 v[6:7], v[28:31], off
	s_waitcnt lgkmcnt(0)
	v_readlane_b32 s21, v252, 6
	v_readlane_b32 s22, v252, 7
	v_readlane_b32 s23, v252, 8
	v_readlane_b32 s26, v252, 11
	v_readlane_b32 s27, v252, 12
	v_readlane_b32 s28, v252, 13
	v_readlane_b32 s29, v252, 14
	v_readlane_b32 s30, v252, 15
	v_readlane_b32 s31, v252, 16
	s_mov_b64 s[6:7], 0
.LBB0_1387:
	s_andn2_b64 vcc, exec, s[6:7]
	s_mov_b32 s6, 0
	s_cbranch_vccnz .LBB0_1413
	v_readlane_b32 s16, v252, 1
	v_readlane_b32 s22, v252, 7
	v_readlane_b32 s23, v252, 8
	s_add_u32 s8, s22, s0
	s_addc_u32 s9, s23, s1
	s_lshl_b32 s0, s2, 10
	s_ashr_i32 s1, s0, 31
	v_readlane_b32 s20, v252, 5
	s_lshl_b64 s[0:1], s[0:1], 2
	v_readlane_b32 s21, v252, 6
	s_add_u32 s6, s20, s0
	s_addc_u32 s7, s21, s1
	s_add_i32 s0, s10, 0xf880
	s_lshr_b32 s0, s0, 1
	s_and_b32 s15, s0, 0x7fc0
	s_lshl_b32 s0, s10, 5
	s_and_b32 s11, s0, 0xfe0
	s_lshl_b32 s0, s11, 2
	s_add_u32 s0, s8, s0
	v_or_b32_e32 v57, s15, v0
	s_addc_u32 s1, s9, 0
	v_lshlrev_b32_e32 v6, 2, v2
	v_mov_b32_e32 v7, v16
	v_lshl_add_u64 v[6:7], s[0:1], 0, v[6:7]
	v_lshlrev_b32_e32 v8, 14, v57
	v_mov_b32_e32 v9, v16
	v_lshl_add_u64 v[6:7], v[6:7], 0, v[8:9]
	s_mov_b32 s0, 0x8000
	v_add_co_u32_e32 v8, vcc, s0, v6
	s_mov_b32 s0, 0x10000
	s_nop 0
	v_addc_co_u32_e32 v9, vcc, 0, v7, vcc
	global_load_dword v53, v[6:7], off nt
	global_load_dword v54, v[8:9], off nt
	v_add_co_u32_e32 v8, vcc, s0, v6
	s_mov_b32 s0, 0x18000
	s_nop 0
	v_addc_co_u32_e32 v9, vcc, 0, v7, vcc
	global_load_dword v55, v[8:9], off nt
	v_add_co_u32_e32 v8, vcc, s0, v6
	s_mov_b32 s0, 0x20000
	s_nop 0
	v_addc_co_u32_e32 v9, vcc, 0, v7, vcc
	global_load_dword v56, v[8:9], off nt
	v_add_co_u32_e32 v8, vcc, s0, v6
	s_mov_b32 s0, 0x28000
	s_nop 0
	v_addc_co_u32_e32 v9, vcc, 0, v7, vcc
	global_load_dword v49, v[8:9], off nt
	v_add_co_u32_e32 v8, vcc, s0, v6
	s_mov_b32 s0, 0x30000
	s_nop 0
	v_addc_co_u32_e32 v9, vcc, 0, v7, vcc
	global_load_dword v50, v[8:9], off nt
	v_add_co_u32_e32 v8, vcc, s0, v6
	s_mov_b32 s0, 0x38000
	s_nop 0
	v_addc_co_u32_e32 v9, vcc, 0, v7, vcc
	global_load_dword v51, v[8:9], off nt
	v_add_co_u32_e32 v8, vcc, s0, v6
	s_mov_b32 s0, 0x40000
	s_nop 0
	v_addc_co_u32_e32 v9, vcc, 0, v7, vcc
	global_load_dword v52, v[8:9], off nt
	v_add_co_u32_e32 v8, vcc, s0, v6
	s_mov_b32 s0, 0x48000
	s_nop 0
	v_addc_co_u32_e32 v9, vcc, 0, v7, vcc
	global_load_dword v45, v[8:9], off nt
	v_add_co_u32_e32 v8, vcc, s0, v6
	s_mov_b32 s0, 0x50000
	s_nop 0
	v_addc_co_u32_e32 v9, vcc, 0, v7, vcc
	global_load_dword v46, v[8:9], off nt
	v_add_co_u32_e32 v8, vcc, s0, v6
	s_mov_b32 s0, 0x58000
	s_nop 0
	v_addc_co_u32_e32 v9, vcc, 0, v7, vcc
	global_load_dword v47, v[8:9], off nt
	v_add_co_u32_e32 v8, vcc, s0, v6
	s_mov_b32 s0, 0x60000
	s_nop 0
	v_addc_co_u32_e32 v9, vcc, 0, v7, vcc
	global_load_dword v48, v[8:9], off nt
	v_add_co_u32_e32 v8, vcc, s0, v6
	s_mov_b32 s0, 0x68000
	s_nop 0
	v_addc_co_u32_e32 v9, vcc, 0, v7, vcc
	global_load_dword v41, v[8:9], off nt
	v_add_co_u32_e32 v8, vcc, s0, v6
	s_mov_b32 s0, 0x70000
	s_nop 0
	v_addc_co_u32_e32 v9, vcc, 0, v7, vcc
	global_load_dword v42, v[8:9], off nt
	v_add_co_u32_e32 v8, vcc, s0, v6
	s_mov_b32 s0, 0x78000
	s_nop 0
	v_addc_co_u32_e32 v9, vcc, 0, v7, vcc
	global_load_dword v43, v[8:9], off nt
	v_add_co_u32_e32 v8, vcc, s0, v6
	s_mov_b32 s0, 0x80000
	s_nop 0
	v_addc_co_u32_e32 v9, vcc, 0, v7, vcc
	global_load_dword v44, v[8:9], off nt
	v_add_co_u32_e32 v8, vcc, s0, v6
	s_mov_b32 s0, 0x88000
	s_nop 0
	v_addc_co_u32_e32 v9, vcc, 0, v7, vcc
	global_load_dword v37, v[8:9], off nt
	v_add_co_u32_e32 v8, vcc, s0, v6
	s_mov_b32 s0, 0x90000
	s_nop 0
	v_addc_co_u32_e32 v9, vcc, 0, v7, vcc
	global_load_dword v38, v[8:9], off nt
	v_add_co_u32_e32 v8, vcc, s0, v6
	s_mov_b32 s0, 0x98000
	s_nop 0
	v_addc_co_u32_e32 v9, vcc, 0, v7, vcc
	global_load_dword v39, v[8:9], off nt
	v_add_co_u32_e32 v8, vcc, s0, v6
	s_mov_b32 s0, 0xa0000
	s_nop 0
	v_addc_co_u32_e32 v9, vcc, 0, v7, vcc
	global_load_dword v40, v[8:9], off nt
	v_add_co_u32_e32 v8, vcc, s0, v6
	s_mov_b32 s0, 0xa8000
	s_nop 0
	v_addc_co_u32_e32 v9, vcc, 0, v7, vcc
	global_load_dword v32, v[8:9], off nt
	v_add_co_u32_e32 v8, vcc, s0, v6
	s_mov_b32 s0, 0xb0000
	s_nop 0
	v_addc_co_u32_e32 v9, vcc, 0, v7, vcc
	global_load_dword v34, v[8:9], off nt
	v_add_co_u32_e32 v8, vcc, s0, v6
	s_mov_b32 s0, 0xb8000
	s_nop 0
	v_addc_co_u32_e32 v9, vcc, 0, v7, vcc
	global_load_dword v35, v[8:9], off nt
	v_add_co_u32_e32 v8, vcc, s0, v6
	s_mov_b32 s0, 0xc0000
	s_nop 0
	v_addc_co_u32_e32 v9, vcc, 0, v7, vcc
	global_load_dword v36, v[8:9], off nt
	v_add_co_u32_e32 v8, vcc, s0, v6
	s_mov_b32 s0, 0xc8000
	s_nop 0
	v_addc_co_u32_e32 v9, vcc, 0, v7, vcc
	global_load_dword v29, v[8:9], off nt
	v_add_co_u32_e32 v8, vcc, s0, v6
	s_mov_b32 s0, 0xd0000
	s_nop 0
	v_addc_co_u32_e32 v9, vcc, 0, v7, vcc
	global_load_dword v30, v[8:9], off nt
	v_add_co_u32_e32 v8, vcc, s0, v6
	s_mov_b32 s0, 0xd8000
	s_nop 0
	v_addc_co_u32_e32 v9, vcc, 0, v7, vcc
	global_load_dword v31, v[8:9], off nt
	v_add_co_u32_e32 v8, vcc, s0, v6
	s_mov_b32 s0, 0xe0000
	s_nop 0
	v_addc_co_u32_e32 v9, vcc, 0, v7, vcc
	global_load_dword v33, v[8:9], off nt
	v_add_co_u32_e32 v8, vcc, s0, v6
	v_readlane_b32 s8, v248, 44
	s_nop 0
	v_addc_co_u32_e32 v9, vcc, 0, v7, vcc
	v_add_co_u32_e32 v58, vcc, 0xe8000, v6
	global_load_dword v8, v[8:9], off nt
	s_nop 0
	v_addc_co_u32_e32 v59, vcc, 0, v7, vcc
	global_load_dword v9, v[58:59], off nt
	v_add_co_u32_e32 v58, vcc, 0xf0000, v6
	v_readlane_b32 s9, v248, 45
	s_nop 0
	v_addc_co_u32_e32 v59, vcc, 0, v7, vcc
	v_add_co_u32_e32 v6, vcc, 0xf8000, v6
	global_load_dword v28, v[58:59], off nt
	s_nop 0
	v_addc_co_u32_e32 v7, vcc, 0, v7, vcc
	global_load_dword v6, v[6:7], off nt
	v_cndmask_b32_e64 v7, 0, 1, s[8:9]
	v_cmp_ne_u32_e64 s[0:1], 1, v7
	s_andn2_b64 vcc, exec, s[8:9]
	v_add_lshl_u32 v7, s15, v0, 2
	v_readlane_b32 s17, v252, 2
	v_readlane_b32 s18, v252, 3
	v_readlane_b32 s19, v252, 4
	v_readlane_b32 s24, v252, 9
	v_readlane_b32 s25, v252, 10
	v_readlane_b32 s26, v252, 11
	v_readlane_b32 s27, v252, 12
	v_readlane_b32 s28, v252, 13
	v_readlane_b32 s29, v252, 14
	v_readlane_b32 s30, v252, 15
	v_readlane_b32 s31, v252, 16
	s_cbranch_vccnz .LBB0_1455
	v_lshlrev_b32_e32 v57, 2, v57
	global_load_dword v57, v57, s[6:7]
	v_add_u32_e32 v59, v5, v10
	global_load_dword v58, v7, s[6:7] offset:8
	s_waitcnt vmcnt(1)
	v_mul_f32_e32 v57, v53, v57
	ds_write_b32 v59, v57
	s_waitcnt vmcnt(0)
	v_mul_f32_e32 v57, v54, v58
	v_add_u32_e32 v58, v5, v17
	ds_write_b32 v58, v57
	global_load_dword v57, v7, s[6:7] offset:16
	global_load_dword v58, v7, s[6:7] offset:24
	s_waitcnt vmcnt(1)
	v_mul_f32_e32 v57, v55, v57
	s_cbranch_execnz .LBB0_1391
